# EpiUp stores via scalar base + 32-bit lane offset (no per-store 64-bit mad); attention loop: dead/duplicate row-sum adds and copies removed, loop-invariant lane offsets hoisted
# speedup vs baseline: 1.0281x; 1.0028x over previous
; #define GAS __attribute__((address_space(1)))
; #define GAS __attribute__((address_space(1)))
; #define ATT_LOAD(j) do { int ra = 64 * (j) + krow0; if (ra > TT - 1) ra = TT - 1; kr0 = *(GAS const u32x4*)(Kh + (size_t)ra * 96 + kch0 * 8); \
;             if (k2) { int rb = 64 * (j) + krow1; if (rb > TT - 1) rb = TT - 1; kr1 = *(GAS const u32x4*)(Kh + (size_t)rb * 96 + kch1 * 8); } \
;             vr = *(GAS const u32x4*)(Vh + 64 * (j) + vch * 8); } while (0)
; template <int VAR> DI void phase_attn(LAS unsigned char* lds, const bf16_t* Q, const bf16_t* K, const bf16_t* VT, bf16_t* O) {
;     ...
;         const int b = bh >> 4, h = bh & 15; const int q0 = qb * 256;
;         const size_t rowb = (size_t)b * TT;
;         const int qlast = (q0 + 255 < TT - 1) ? q0 + 255 : TT - 1; const int ntiles = (qlast >> 6) + 1;
;         const int qw0 = q0 + 32 * wid; const bool wvalid = qw0 < TT;
;         int my_last = (qw0 + 31) >> 6; if (my_last > ntiles - 1) my_last = ntiles - 1; if (!wvalid) my_last = -1;
;         int tq = qw0 + r32; if (tq > TT - 1) tq = TT - 1;
;         bf16x8 qr[6];
;         { const bf16_t* qp = Q + (rowb + tq) * 1536 + h * 96 + 8 * hi;
; #pragma unroll
;           for (int s = 0; s < 6; ++s) qr[s] = *(GAS const bf16x8*)(qp + 16 * s); }
;         const bf16_t* Kh = K + (size_t)bh * TT * 96; const bf16_t* Vh = VT + (size_t)(bh * 64 + vd) * 4160;
;         u32x4 kr0, kr1 = {0u, 0u, 0u, 0u}, vr;
;     ...
;         ATT_LOAD(0); ATT_STORE(0);
.LBB0_42:
	s_lshl_b32 s41, s8, 8
	s_add_i32 s36, s41, s17
	v_or_b32_e32 v201, s36, v134
	v_min_i32_e32 v0, 0x100f, v201
	s_ashr_i32 s37, s40, 4
	v_ashrrev_i32_e32 v1, 31, v0
	v_mov_b32_e32 v2, 0x1010
	v_mad_i64_i32 v[0:1], s[0:1], s37, v2, v[0:1]
	v_mov_b64_e32 v[2:3], s[28:29]
	s_and_b32 s19, s40, 15
	v_mad_u64_u32 v[2:3], s[0:1], v0, s84, v[2:3]
	v_mad_i32_i24 v3, v1, s84, v3
	s_mul_i32 s98, s19, 0xc0
	v_lshl_add_u64 v[0:1], v[2:3], 0, s[98:99]
	v_lshl_add_u64 v[0:1], v[0:1], 0, v[64:65]
	s_mul_i32 s1, s40, 0xc0c00
	v_mov_b32_e32 v94, v65
	v_mov_b32_e32 v95, v65
	v_mov_b32_e32 v96, v65
	v_mov_b32_e32 v97, v65
	global_load_dwordx4 v[66:69], v[0:1], off
	global_load_dwordx4 v[70:73], v[0:1], off offset:32
	global_load_dwordx4 v[74:77], v[0:1], off offset:64
	global_load_dwordx4 v[78:81], v[0:1], off offset:96
	global_load_dwordx4 v[82:85], v[0:1], off offset:128
	global_load_dwordx4 v[86:89], v[0:1], off offset:160
	s_mul_hi_i32 s0, s40, 0xc0c00
	s_add_u32 s8, s10, s1
	s_addc_u32 s9, s11, s0
	s_mov_b64 s[100:101], s[8:9]
	v_lshlrev_b32_e32 v193, 4, v157
	v_add_u32_e32 v194, 0x6800, v168
	v_lshl_add_u64 v[0:1], s[8:9], 0, v[136:137]
	v_lshl_add_u64 v[0:1], v[138:139], 1, v[0:1]
	global_load_dwordx4 v[90:93], v[0:1], off
	s_and_saveexec_b64 s[0:1], s[6:7]
	s_cbranch_execz .LBB0_44
	v_lshl_add_u64 v[0:1], s[8:9], 0, v[140:141]
	v_lshl_add_u64 v[0:1], v[142:143], 1, v[0:1]
	global_load_dwordx4 v[94:97], v[0:1], off

.LBB0_62:
	s_or_b64 exec, exec, s[0:1]
	s_mulk_i32 s8, 0x2400
	v_add_u32_e32 v32, s8, v194
	s_waitcnt vmcnt(0)
	ds_write2_b64 v32, v[98:99], v[100:101] offset1:2

; #define ATT_LOAD(j) do { int ra = 64 * (j) + krow0; if (ra > TT - 1) ra = TT - 1; kr0 = *(GAS const u32x4*)(Kh + (size_t)ra * 96 + kch0 * 8); \
;             if (k2) { int rb = 64 * (j) + krow1; if (rb > TT - 1) rb = TT - 1; kr1 = *(GAS const u32x4*)(Kh + (size_t)rb * 96 + kch1 * 8); } \
;             vr = *(GAS const u32x4*)(Vh + 64 * (j) + vch * 8); } while (0)
; template <int VAR> DI void phase_attn(LAS unsigned char* lds, const bf16_t* Q, const bf16_t* K, const bf16_t* VT, bf16_t* O) {
;     ...
;         for (int j = 0; j < ntiles; ++j) {
;             const int buf = j & 1;
;             if (VAR != 3 && j + 1 < ntiles) ATT_LOAD(j + 1);
.LBB0_64:
	s_add_i32 s42, s42, 1
	s_cmp_lt_i32 s42, s59
	s_cselect_b64 s[0:1], -1, 0
	s_cmp_ge_i32 s42, s59
	s_cbranch_scc1 .LBB0_69
	s_mul_i32 s9, s98, 0xc0
	s_add_u32 vcc_lo, s100, s9
	s_addc_u32 vcc_hi, s101, 0
	global_load_dwordx4 v[90:93], v193, vcc
	s_add_u32 vcc_lo, vcc_lo, 0x2000
	s_addc_u32 vcc_hi, vcc_hi, 0
	s_and_saveexec_b64 s[8:9], s[6:7]
	s_cbranch_execz .LBB0_67
	global_load_dwordx4 v[94:97], v193, vcc

; __device__ __forceinline__ unsigned pk2(float lo, float hi) { f32x2v v = {lo, hi}; bf16x2v b = __builtin_convertvector(v, bf16x2v); return __builtin_bit_cast(unsigned, b); }
; DI f32x16 mfma32(bf16x8 a, bf16x8 b, f32x16 c) { return __builtin_amdgcn_mfma_f32_32x32x16_bf16(a, b, c, 0, 0, 0); }
; template <int VAR> DI void phase_attn(LAS unsigned char* lds, const bf16_t* Q, const bf16_t* K, const bf16_t* VT, bf16_t* O) {
;     ...
;                 float ls = 0.f;
; #pragma unroll
;                 for (int r = 0; r < 16; ++r) { if (VAR != 1) { p0[r] = __builtin_amdgcn_exp2f(p0[r]); p1[r] = __builtin_amdgcn_exp2f(p1[r]); } }
; #pragma unroll
;                 for (int r = 0; r < 16; r += 2) ls += (p0[r] + p0[r + 1]) + (p1[r] + p1[r + 1]);
;                 lrun += ls;
;                 bf16x8 pf[4];
;                 { u32x4 w;
;                   w.x = pk2(p0[0], p0[1]); w.y = pk2(p0[2], p0[3]); w.z = pk2(p0[4], p0[5]); w.w = pk2(p0[6], p0[7]); pf[0] = __builtin_bit_cast(bf16x8, w);
;                   w.x = pk2(p0[8], p0[9]); w.y = pk2(p0[10], p0[11]); w.z = pk2(p0[12], p0[13]); w.w = pk2(p0[14], p0[15]); pf[1] = __builtin_bit_cast(bf16x8, w);
;                   w.x = pk2(p1[0], p1[1]); w.y = pk2(p1[2], p1[3]); w.z = pk2(p1[4], p1[5]); w.w = pk2(p1[6], p1[7]); pf[2] = __builtin_bit_cast(bf16x8, w);
;                   w.x = pk2(p1[8], p1[9]); w.y = pk2(p1[10], p1[11]); w.z = pk2(p1[12], p1[13]); w.w = pk2(p1[14], p1[15]); pf[3] = __builtin_bit_cast(bf16x8, w); }
; #pragma unroll
;                 for (int f = 0; f < 4; ++f) { if (VAR == 2) { o0[f] += __builtin_bit_cast(f32x4, va[2 * f])[0] * __builtin_bit_cast(f32x4, pf[f])[1]; o1[f] += __builtin_bit_cast(f32x4, va[2 * f + 1])[2]; } else { o0 = mfma32(va[2 * f], pf[f], o0); o1 = mfma32(va[2 * f + 1], pf[f], o1); } }
.LBB0_74:
	v_exp_f32_e32 v173, v48
	v_exp_f32_e32 v49, v49
	v_exp_f32_e32 v172, v50
	v_exp_f32_e32 v48, v51
	v_exp_f32_e32 v50, v52
	v_exp_f32_e32 v51, v36
	v_exp_f32_e32 v36, v53
	v_exp_f32_e32 v53, v54
	v_exp_f32_e32 v210, v55
	v_exp_f32_e32 v175, v32
	v_exp_f32_e32 v209, v33
	v_exp_f32_e32 v174, v34
	v_exp_f32_e32 v208, v35
	v_cvt_pk_bf16_f32 v32, v173, v49
	v_cvt_pk_bf16_f32 v33, v172, v48
	v_cvt_pk_bf16_f32 v34, v50, v36
	v_cvt_pk_bf16_f32 v35, v53, v210
	v_exp_f32_e32 v206, v38
	v_exp_f32_e32 v38, v56
	s_waitcnt lgkmcnt(7)
	v_mfma_f32_32x32x16_bf16 v[0:15], v[130:133], v[32:35], v[0:15]
	v_exp_f32_e32 v52, v57
	v_exp_f32_e32 v56, v58
	v_exp_f32_e32 v57, v42
	v_exp_f32_e32 v42, v59
	v_exp_f32_e32 v59, v60
	v_exp_f32_e32 v130, v44
	v_exp_f32_e32 v61, v61
	s_waitcnt lgkmcnt(5)
	v_mfma_f32_32x32x16_bf16 v[16:31], v[126:129], v[32:35], v[16:31]
	v_exp_f32_e32 v44, v62
	v_exp_f32_e32 v58, v63
	v_cvt_pk_bf16_f32 v32, v38, v52
	v_cvt_pk_bf16_f32 v33, v56, v42
	v_cvt_pk_bf16_f32 v34, v59, v61
	v_cvt_pk_bf16_f32 v35, v44, v58
	v_exp_f32_e32 v37, v37
	v_exp_f32_e32 v211, v39
	v_mfma_f32_32x32x16_bf16 v[0:15], v[122:125], v[32:35], v[0:15]
	v_add_f32_e64 v48, v172, v48
	v_add_f32_e64 v49, v173, v49
	v_add_f32_e64 v62, v174, v208
	v_add_f32_e64 v63, v175, v209
	v_exp_f32_e32 v40, v40
	v_add_f32_e32 v48, v48, v62
	v_add_f32_e32 v49, v49, v63
	v_exp_f32_e32 v54, v41
	v_add_f32_e32 v55, v48, v49
	s_waitcnt lgkmcnt(4)
	v_mfma_f32_32x32x16_bf16 v[16:31], v[118:121], v[32:35], v[16:31]
	v_add_f32_e64 v32, v50, v36
	v_add_f32_e64 v33, v51, v37
	v_cvt_pk_bf16_f32 v34, v51, v37
	v_add_f32_e64 v49, v32, v33
	v_cvt_pk_bf16_f32 v32, v175, v209
	v_cvt_pk_bf16_f32 v33, v174, v208
	v_cvt_pk_bf16_f32 v35, v206, v211
	v_exp_f32_e32 v43, v43
	v_exp_f32_e32 v122, v45
	s_waitcnt lgkmcnt(3)
	v_mfma_f32_32x32x16_bf16 v[0:15], v[114:117], v[32:35], v[0:15]
	v_exp_f32_e32 v46, v46
	v_exp_f32_e32 v60, v47
	v_add_f32_e32 v39, v53, v210
	v_add_f32_e32 v53, v206, v211
	v_add_f32_e32 v36, v38, v52
	v_add_f32_e32 v37, v39, v53
	v_add_f32_e32 v38, v40, v54
	v_add_f32_e32 v39, v49, v55
	s_waitcnt lgkmcnt(1)
	v_mfma_f32_32x32x16_bf16 v[16:31], v[110:113], v[32:35], v[16:31]
	v_add_f32_e64 v32, v56, v42
	v_add_f32_e64 v33, v57, v43
	v_add_f32_e64 v36, v36, v38
	v_add_f32_e64 v37, v37, v39
	v_add_f32_e64 v39, v32, v33
	v_cvt_pk_bf16_f32 v32, v40, v54
	v_cvt_pk_bf16_f32 v33, v57, v43
	v_cvt_pk_bf16_f32 v34, v130, v122
	v_cvt_pk_bf16_f32 v35, v46, v60
	v_add_f32_e32 v37, v36, v37
	v_add_f32_e32 v45, v59, v61
	v_mfma_f32_32x32x16_bf16 v[0:15], v[106:109], v[32:35], v[0:15]
	v_add_f32_e32 v59, v130, v122
	v_add_f32_e64 v40, v44, v58
	v_add_f32_e64 v41, v45, v59
	v_add_f32_e32 v36, v46, v60
	v_add_f32_e32 v37, v39, v37
	s_nop 0
	v_add_f32_e32 v36, v40, v36
	v_add_f32_e32 v37, v41, v37
	s_waitcnt lgkmcnt(0)
	v_mfma_f32_32x32x16_bf16 v[16:31], v[102:105], v[32:35], v[16:31]
	v_add_f32_e32 v36, v36, v37
	v_add_f32_e32 v203, v203, v36
	s_andn2_b64 vcc, exec, s[0:1]
	s_cbranch_vccnz .LBB0_63

; #define GAS __attribute__((address_space(1)))
; __device__ __forceinline__ unsigned pk2(float lo, float hi) { f32x2v v = {lo, hi}; bf16x2v b = __builtin_convertvector(v, bf16x2v); return __builtin_bit_cast(unsigned, b); }
; #define GAS __attribute__((address_space(1)))
;     __device__ __forceinline__ void operator()(const f32x4 (&acc)[2][2][4][2], const Unit& u, int wr, int wc, int fr, int fq) const {
;     ...
;                     const int row = rb + 128 * ai + 64 * wr + 16 * m + fr; const unsigned f = flags >> (3 * (ai * 4 + m));
;                     if (bstart) { if (f & 2u) { pA1 = zero; pG1 = zero; }
;                                   if (f & 4u) { pA2 = zero; pG2 = zero; } }
;                     const f32x2v va = wA0 * pA2 + wA1 * pA1 + wA2 * ua + bA, vg = wG0 * pG2 + wG1 * pG1 + wG2 * ug + bG;
;                     const float o0 = va[0] * __builtin_amdgcn_rcpf(1.f + __expf(-va[0])) * vg[0], o1 = va[1] * __builtin_amdgcn_rcpf(1.f + __expf(-va[1])) * vg[1];
;                     if (allemit) *(GAS unsigned*)(G + (size_t)row * 2816 + ca0) = pk2(o0, o1);
;                     else if (f & 1u) *(GAS unsigned*)(G + (size_t)row * 2816 + ca0) = pk2(o0, o1);
.LBB0_233:
	v_or_b32_e32 v154, s6, v210
	s_cmp_eq_u64 s[40:41], s[84:85]
	v_mul_lo_u32 v155, v220, s98
	s_cselect_b64 s[90:91], -1, 0
	v_lshl_add_u32 v154, v154, 1, v155
	s_or_b64 s[84:85], s[90:91], s[68:69]
	s_and_saveexec_b64 s[6:7], s[84:85]
	s_cbranch_execz .LBB0_235
	s_waitcnt lgkmcnt(3)
	v_pk_mul_f32 v[198:199], v[144:145], v[198:199]
	s_waitcnt lgkmcnt(2)
	v_pk_fma_f32 v[194:195], v[132:133], v[194:195], v[198:199]
	s_waitcnt lgkmcnt(1)
	v_pk_fma_f32 v[186:187], v[186:187], v[136:137], v[194:195]
	s_waitcnt lgkmcnt(0)
	v_pk_add_f32 v[186:187], v[140:141], v[186:187]
	s_nop 0
	v_mul_f32_e32 v151, 0xbfb8aa3b, v187
	v_exp_f32_e32 v151, v151
	v_mul_f32_e32 v194, 0xbfb8aa3b, v186
	v_exp_f32_e32 v198, v194
	v_pk_mul_f32 v[194:195], v[146:147], v[196:197]
	v_add_f32_e32 v151, 1.0, v151
	v_rcp_f32_e32 v197, v151
	v_add_f32_e32 v151, 1.0, v198
	v_rcp_f32_e32 v196, v151
	v_pk_fma_f32 v[192:193], v[134:135], v[192:193], v[194:195]
	v_pk_mul_f32 v[186:187], v[186:187], v[196:197]
	v_pk_fma_f32 v[184:185], v[184:185], v[138:139], v[192:193]
	s_nop 0
	v_pk_add_f32 v[184:185], v[142:143], v[184:185]
	s_nop 0
	v_pk_mul_f32 v[184:185], v[184:185], v[186:187]
	s_nop 0
	v_cvt_pk_bf16_f32 v151, v184, v185
	s_nop 0
	global_store_dword v154, v151, s[86:87]

; #define GAS __attribute__((address_space(1)))
; __device__ __forceinline__ unsigned pk2(float lo, float hi) { f32x2v v = {lo, hi}; bf16x2v b = __builtin_convertvector(v, bf16x2v); return __builtin_bit_cast(unsigned, b); }
; #define GAS __attribute__((address_space(1)))
;     __device__ __forceinline__ void operator()(const f32x4 (&acc)[2][2][4][2], const Unit& u, int wr, int wc, int fr, int fq) const {
;     ...
;                     const int row = rb + 128 * ai + 64 * wr + 16 * m + fr; const unsigned f = flags >> (3 * (ai * 4 + m));
;                     if (bstart) { if (f & 2u) { pA1 = zero; pG1 = zero; }
;                                   if (f & 4u) { pA2 = zero; pG2 = zero; } }
;                     const f32x2v va = wA0 * pA2 + wA1 * pA1 + wA2 * ua + bA, vg = wG0 * pG2 + wG1 * pG1 + wG2 * ug + bG;
;                     const float o0 = va[0] * __builtin_amdgcn_rcpf(1.f + __expf(-va[0])) * vg[0], o1 = va[1] * __builtin_amdgcn_rcpf(1.f + __expf(-va[1])) * vg[1];
;                     if (allemit) *(GAS unsigned*)(G + (size_t)row * 2816 + ca0) = pk2(o0, o1);
;                     else if (f & 1u) *(GAS unsigned*)(G + (size_t)row * 2816 + ca0) = pk2(o0, o1);
.LBB0_239:
	v_add_u32_e32 v224, 16, v220
	s_or_b64 s[62:63], s[90:91], s[62:63]
	s_and_saveexec_b64 s[6:7], s[62:63]
	s_cbranch_execz .LBB0_241
	s_waitcnt lgkmcnt(3)
	v_pk_mul_f32 v[198:199], v[144:145], v[198:199]
	s_waitcnt lgkmcnt(2)
	v_pk_fma_f32 v[194:195], v[132:133], v[194:195], v[198:199]
	s_waitcnt lgkmcnt(1)
	v_pk_fma_f32 v[186:187], v[186:187], v[136:137], v[194:195]
	s_waitcnt lgkmcnt(0)
	v_pk_add_f32 v[186:187], v[140:141], v[186:187]
	s_nop 0
	v_mul_f32_e32 v148, 0xbfb8aa3b, v187
	v_exp_f32_e32 v148, v148
	v_mul_f32_e32 v194, 0xbfb8aa3b, v186
	v_exp_f32_e32 v198, v194
	v_pk_mul_f32 v[194:195], v[146:147], v[196:197]
	v_add_f32_e32 v148, 1.0, v148
	v_rcp_f32_e32 v197, v148
	v_add_f32_e32 v148, 1.0, v198
	v_rcp_f32_e32 v196, v148
	v_pk_fma_f32 v[192:193], v[134:135], v[192:193], v[194:195]
	v_pk_mul_f32 v[186:187], v[186:187], v[196:197]
	v_pk_fma_f32 v[150:151], v[150:151], v[138:139], v[192:193]
	s_nop 0
	v_pk_add_f32 v[150:151], v[142:143], v[150:151]
	s_nop 0
	v_pk_mul_f32 v[150:151], v[150:151], v[186:187]
	s_nop 0
	v_cvt_pk_bf16_f32 v148, v150, v151
	v_add_u32_e32 v150, 0x16000, v154
	global_store_dword v150, v148, s[86:87]

; #define GAS __attribute__((address_space(1)))
; __device__ __forceinline__ unsigned pk2(float lo, float hi) { f32x2v v = {lo, hi}; bf16x2v b = __builtin_convertvector(v, bf16x2v); return __builtin_bit_cast(unsigned, b); }
; #define GAS __attribute__((address_space(1)))
;     __device__ __forceinline__ void operator()(const f32x4 (&acc)[2][2][4][2], const Unit& u, int wr, int wc, int fr, int fq) const {
;     ...
;                     const int row = rb + 128 * ai + 64 * wr + 16 * m + fr; const unsigned f = flags >> (3 * (ai * 4 + m));
;                     if (bstart) { if (f & 2u) { pA1 = zero; pG1 = zero; }
;                                   if (f & 4u) { pA2 = zero; pG2 = zero; } }
;                     const f32x2v va = wA0 * pA2 + wA1 * pA1 + wA2 * ua + bA, vg = wG0 * pG2 + wG1 * pG1 + wG2 * ug + bG;
;                     const float o0 = va[0] * __builtin_amdgcn_rcpf(1.f + __expf(-va[0])) * vg[0], o1 = va[1] * __builtin_amdgcn_rcpf(1.f + __expf(-va[1])) * vg[1];
;                     if (allemit) *(GAS unsigned*)(G + (size_t)row * 2816 + ca0) = pk2(o0, o1);
;                     else if (f & 1u) *(GAS unsigned*)(G + (size_t)row * 2816 + ca0) = pk2(o0, o1);
.LBB0_245:
	v_add_u32_e32 v225, 32, v220
	s_or_b64 s[6:7], s[90:91], s[58:59]
	s_and_saveexec_b64 s[50:51], s[6:7]
	s_cbranch_execz .LBB0_247
	s_waitcnt lgkmcnt(3)
	v_pk_mul_f32 v[198:199], v[144:145], v[198:199]
	s_waitcnt lgkmcnt(2)
	v_pk_fma_f32 v[194:195], v[132:133], v[194:195], v[198:199]
	s_waitcnt lgkmcnt(1)
	v_pk_fma_f32 v[150:151], v[150:151], v[136:137], v[194:195]
	s_waitcnt lgkmcnt(0)
	v_pk_add_f32 v[150:151], v[140:141], v[150:151]
	s_nop 0
	v_mul_f32_e32 v185, 0xbfb8aa3b, v151
	v_exp_f32_e32 v185, v185
	v_mul_f32_e32 v194, 0xbfb8aa3b, v150
	v_exp_f32_e32 v198, v194
	v_pk_mul_f32 v[194:195], v[146:147], v[196:197]
	v_add_f32_e32 v185, 1.0, v185
	v_rcp_f32_e32 v197, v185
	v_add_f32_e32 v185, 1.0, v198
	v_rcp_f32_e32 v196, v185
	v_pk_fma_f32 v[192:193], v[134:135], v[192:193], v[194:195]
	v_pk_mul_f32 v[150:151], v[150:151], v[196:197]
	v_pk_fma_f32 v[148:149], v[148:149], v[138:139], v[192:193]
	s_nop 0
	v_pk_add_f32 v[148:149], v[142:143], v[148:149]
	s_nop 0
	v_pk_mul_f32 v[148:149], v[148:149], v[150:151]
	s_nop 0
	v_cvt_pk_bf16_f32 v150, v148, v149
	v_add_u32_e32 v148, 0x2c000, v154
	global_store_dword v148, v150, s[86:87]

; #define GAS __attribute__((address_space(1)))
; __device__ __forceinline__ unsigned pk2(float lo, float hi) { f32x2v v = {lo, hi}; bf16x2v b = __builtin_convertvector(v, bf16x2v); return __builtin_bit_cast(unsigned, b); }
; #define GAS __attribute__((address_space(1)))
;     __device__ __forceinline__ void operator()(const f32x4 (&acc)[2][2][4][2], const Unit& u, int wr, int wc, int fr, int fq) const {
;     ...
;                     const int row = rb + 128 * ai + 64 * wr + 16 * m + fr; const unsigned f = flags >> (3 * (ai * 4 + m));
;                     if (bstart) { if (f & 2u) { pA1 = zero; pG1 = zero; }
;                                   if (f & 4u) { pA2 = zero; pG2 = zero; } }
;                     const f32x2v va = wA0 * pA2 + wA1 * pA1 + wA2 * ua + bA, vg = wG0 * pG2 + wG1 * pG1 + wG2 * ug + bG;
;                     const float o0 = va[0] * __builtin_amdgcn_rcpf(1.f + __expf(-va[0])) * vg[0], o1 = va[1] * __builtin_amdgcn_rcpf(1.f + __expf(-va[1])) * vg[1];
;                     if (allemit) *(GAS unsigned*)(G + (size_t)row * 2816 + ca0) = pk2(o0, o1);
;                     else if (f & 1u) *(GAS unsigned*)(G + (size_t)row * 2816 + ca0) = pk2(o0, o1);
.LBB0_251:
	v_add_u32_e32 v223, 48, v220
	s_or_b64 s[16:17], s[90:91], s[16:17]
	s_and_saveexec_b64 s[50:51], s[16:17]
	s_cbranch_execz .LBB0_253
	s_waitcnt lgkmcnt(3)
	v_pk_mul_f32 v[198:199], v[144:145], v[198:199]
	s_waitcnt lgkmcnt(2)
	v_pk_fma_f32 v[194:195], v[132:133], v[194:195], v[198:199]
	s_waitcnt lgkmcnt(1)
	v_pk_fma_f32 v[150:151], v[150:151], v[136:137], v[194:195]
	v_pk_mul_f32 v[194:195], v[146:147], v[196:197]
	s_waitcnt lgkmcnt(0)
	v_pk_add_f32 v[150:151], v[140:141], v[150:151]
	v_pk_fma_f32 v[192:193], v[134:135], v[192:193], v[194:195]
	v_mul_f32_e32 v185, 0xbfb8aa3b, v151
	v_exp_f32_e32 v185, v185
	v_mul_f32_e32 v187, 0xbfb8aa3b, v150
	v_exp_f32_e32 v187, v187
	v_pk_fma_f32 v[148:149], v[148:149], v[138:139], v[192:193]
	v_add_f32_e32 v185, 1.0, v185
	v_rcp_f32_e32 v197, v185
	v_add_f32_e32 v185, 1.0, v187
	v_rcp_f32_e32 v196, v185
	v_pk_add_f32 v[148:149], v[142:143], v[148:149]
	v_pk_mul_f32 v[150:151], v[150:151], v[196:197]
	s_nop 0
	v_pk_mul_f32 v[148:149], v[148:149], v[150:151]
	s_nop 0
	v_cvt_pk_bf16_f32 v150, v148, v149
	v_add_u32_e32 v148, 0x42000, v154
	global_store_dword v148, v150, s[86:87]

; #define GAS __attribute__((address_space(1)))
; __device__ __forceinline__ unsigned pk2(float lo, float hi) { f32x2v v = {lo, hi}; bf16x2v b = __builtin_convertvector(v, bf16x2v); return __builtin_bit_cast(unsigned, b); }
; #define GAS __attribute__((address_space(1)))
;     __device__ __forceinline__ void operator()(const f32x4 (&acc)[2][2][4][2], const Unit& u, int wr, int wc, int fr, int fq) const {
;     ...
;                     const int row = rb + 128 * ai + 64 * wr + 16 * m + fr; const unsigned f = flags >> (3 * (ai * 4 + m));
;                     if (bstart) { if (f & 2u) { pA1 = zero; pG1 = zero; }
;                                   if (f & 4u) { pA2 = zero; pG2 = zero; } }
;                     const f32x2v va = wA0 * pA2 + wA1 * pA1 + wA2 * ua + bA, vg = wG0 * pG2 + wG1 * pG1 + wG2 * ug + bG;
;                     const float o0 = va[0] * __builtin_amdgcn_rcpf(1.f + __expf(-va[0])) * vg[0], o1 = va[1] * __builtin_amdgcn_rcpf(1.f + __expf(-va[1])) * vg[1];
;                     if (allemit) *(GAS unsigned*)(G + (size_t)row * 2816 + ca0) = pk2(o0, o1);
;                     else if (f & 1u) *(GAS unsigned*)(G + (size_t)row * 2816 + ca0) = pk2(o0, o1);
.LBB0_259:
	v_and_b32_e32 v185, 0x1000, v153
	v_cmp_ne_u32_e32 vcc, 0, v185
	s_or_b64 s[58:59], s[90:91], vcc
	s_and_saveexec_b64 s[56:57], s[58:59]
	s_cbranch_execz .LBB0_261
	s_waitcnt lgkmcnt(3)
	v_pk_mul_f32 v[198:199], v[144:145], v[198:199]
	v_pk_mul_f32 v[150:151], v[146:147], v[150:151]
	s_waitcnt lgkmcnt(2)
	v_pk_fma_f32 v[196:197], v[132:133], v[196:197], v[198:199]
	v_pk_fma_f32 v[148:149], v[134:135], v[148:149], v[150:151]
	s_waitcnt lgkmcnt(1)
	v_pk_fma_f32 v[194:195], v[194:195], v[136:137], v[196:197]
	v_pk_fma_f32 v[148:149], v[192:193], v[138:139], v[148:149]
	s_waitcnt lgkmcnt(0)
	v_pk_add_f32 v[194:195], v[140:141], v[194:195]
	v_pk_add_f32 v[148:149], v[142:143], v[148:149]
	v_mul_f32_e32 v185, 0xbfb8aa3b, v195
	v_exp_f32_e32 v185, v185
	v_mul_f32_e32 v187, 0xbfb8aa3b, v194
	v_exp_f32_e32 v187, v187
	v_add_f32_e32 v185, 1.0, v185
	v_rcp_f32_e32 v197, v185
	v_add_f32_e32 v185, 1.0, v187
	v_rcp_f32_e32 v196, v185
	s_nop 0
	v_pk_mul_f32 v[150:151], v[194:195], v[196:197]
	s_nop 0
	v_pk_mul_f32 v[148:149], v[148:149], v[150:151]
	s_nop 0
	v_cvt_pk_bf16_f32 v150, v148, v149
	v_add_u32_e32 v148, 0xb0000, v154
	global_store_dword v148, v150, s[86:87]

; #define GAS __attribute__((address_space(1)))
; __device__ __forceinline__ unsigned pk2(float lo, float hi) { f32x2v v = {lo, hi}; bf16x2v b = __builtin_convertvector(v, bf16x2v); return __builtin_bit_cast(unsigned, b); }
; #define GAS __attribute__((address_space(1)))
;     __device__ __forceinline__ void operator()(const f32x4 (&acc)[2][2][4][2], const Unit& u, int wr, int wc, int fr, int fq) const {
;     ...
;                     const int row = rb + 128 * ai + 64 * wr + 16 * m + fr; const unsigned f = flags >> (3 * (ai * 4 + m));
;                     if (bstart) { if (f & 2u) { pA1 = zero; pG1 = zero; }
;                                   if (f & 4u) { pA2 = zero; pG2 = zero; } }
;                     const f32x2v va = wA0 * pA2 + wA1 * pA1 + wA2 * ua + bA, vg = wG0 * pG2 + wG1 * pG1 + wG2 * ug + bG;
;                     const float o0 = va[0] * __builtin_amdgcn_rcpf(1.f + __expf(-va[0])) * vg[0], o1 = va[1] * __builtin_amdgcn_rcpf(1.f + __expf(-va[1])) * vg[1];
;                     if (allemit) *(GAS unsigned*)(G + (size_t)row * 2816 + ca0) = pk2(o0, o1);
;                     else if (f & 1u) *(GAS unsigned*)(G + (size_t)row * 2816 + ca0) = pk2(o0, o1);
.LBB0_265:
	v_and_b32_e32 v189, 0x8000, v153
	v_cmp_ne_u32_e32 vcc, 0, v189
	s_or_b64 s[56:57], s[90:91], vcc
	s_and_saveexec_b64 s[54:55], s[56:57]
	s_cbranch_execz .LBB0_267
	s_waitcnt lgkmcnt(3)
	v_pk_mul_f32 v[198:199], v[144:145], v[198:199]
	s_waitcnt lgkmcnt(2)
	v_pk_fma_f32 v[194:195], v[132:133], v[194:195], v[198:199]
	s_waitcnt lgkmcnt(1)
	v_pk_fma_f32 v[150:151], v[150:151], v[136:137], v[194:195]
	v_pk_mul_f32 v[194:195], v[146:147], v[196:197]
	s_waitcnt lgkmcnt(0)
	v_pk_add_f32 v[150:151], v[140:141], v[150:151]
	v_pk_fma_f32 v[192:193], v[134:135], v[192:193], v[194:195]
	v_mul_f32_e32 v189, 0xbfb8aa3b, v151
	v_exp_f32_e32 v189, v189
	v_mul_f32_e32 v191, 0xbfb8aa3b, v150
	v_exp_f32_e32 v191, v191
	v_pk_fma_f32 v[148:149], v[148:149], v[138:139], v[192:193]
	v_add_f32_e32 v189, 1.0, v189
	v_rcp_f32_e32 v197, v189
	v_add_f32_e32 v189, 1.0, v191
	v_rcp_f32_e32 v196, v189
	v_pk_add_f32 v[148:149], v[142:143], v[148:149]
	v_pk_mul_f32 v[150:151], v[150:151], v[196:197]
	s_nop 0
	v_pk_mul_f32 v[148:149], v[148:149], v[150:151]
	s_nop 0
	v_cvt_pk_bf16_f32 v150, v148, v149
	v_add_u32_e32 v148, 0xc6000, v154
	global_store_dword v148, v150, s[86:87]

; #define GAS __attribute__((address_space(1)))
; __device__ __forceinline__ unsigned pk2(float lo, float hi) { f32x2v v = {lo, hi}; bf16x2v b = __builtin_convertvector(v, bf16x2v); return __builtin_bit_cast(unsigned, b); }
; #define GAS __attribute__((address_space(1)))
;     __device__ __forceinline__ void operator()(const f32x4 (&acc)[2][2][4][2], const Unit& u, int wr, int wc, int fr, int fq) const {
;     ...
;                     const int row = rb + 128 * ai + 64 * wr + 16 * m + fr; const unsigned f = flags >> (3 * (ai * 4 + m));
;                     if (bstart) { if (f & 2u) { pA1 = zero; pG1 = zero; }
;                                   if (f & 4u) { pA2 = zero; pG2 = zero; } }
;                     const f32x2v va = wA0 * pA2 + wA1 * pA1 + wA2 * ua + bA, vg = wG0 * pG2 + wG1 * pG1 + wG2 * ug + bG;
;                     const float o0 = va[0] * __builtin_amdgcn_rcpf(1.f + __expf(-va[0])) * vg[0], o1 = va[1] * __builtin_amdgcn_rcpf(1.f + __expf(-va[1])) * vg[1];
;                     if (allemit) *(GAS unsigned*)(G + (size_t)row * 2816 + ca0) = pk2(o0, o1);
;                     else if (f & 1u) *(GAS unsigned*)(G + (size_t)row * 2816 + ca0) = pk2(o0, o1);
.LBB0_271:
	v_and_b32_e32 v185, 0x40000, v67
	v_cmp_ne_u32_e32 vcc, 0, v185
	s_or_b64 s[68:69], s[90:91], vcc
	s_and_saveexec_b64 s[52:53], s[68:69]
	s_cbranch_execz .LBB0_273
	s_waitcnt lgkmcnt(3)
	v_pk_mul_f32 v[200:201], v[144:145], v[200:201]
	s_waitcnt lgkmcnt(2)
	v_pk_fma_f32 v[196:197], v[132:133], v[196:197], v[200:201]
	s_waitcnt lgkmcnt(1)
	v_pk_fma_f32 v[150:151], v[150:151], v[136:137], v[196:197]
	v_pk_mul_f32 v[196:197], v[146:147], v[198:199]
	s_waitcnt lgkmcnt(0)
	v_pk_add_f32 v[150:151], v[140:141], v[150:151]
	v_pk_fma_f32 v[194:195], v[134:135], v[194:195], v[196:197]
	v_mul_f32_e32 v185, 0xbfb8aa3b, v151
	v_exp_f32_e32 v185, v185
	v_mul_f32_e32 v187, 0xbfb8aa3b, v150
	v_exp_f32_e32 v187, v187
	v_pk_fma_f32 v[148:149], v[148:149], v[138:139], v[194:195]
	v_add_f32_e32 v185, 1.0, v185
	v_rcp_f32_e32 v199, v185
	v_add_f32_e32 v185, 1.0, v187
	v_rcp_f32_e32 v198, v185
	v_pk_add_f32 v[148:149], v[142:143], v[148:149]
	v_pk_mul_f32 v[150:151], v[150:151], v[198:199]
	s_nop 0
	v_pk_mul_f32 v[148:149], v[148:149], v[150:151]
	s_nop 0
	v_cvt_pk_bf16_f32 v150, v148, v149
	v_add_u32_e32 v148, 0xdc000, v154
	global_store_dword v148, v150, s[86:87]

; #define GAS __attribute__((address_space(1)))
; __device__ __forceinline__ unsigned pk2(float lo, float hi) { f32x2v v = {lo, hi}; bf16x2v b = __builtin_convertvector(v, bf16x2v); return __builtin_bit_cast(unsigned, b); }
; #define GAS __attribute__((address_space(1)))
;     __device__ __forceinline__ void operator()(const f32x4 (&acc)[2][2][4][2], const Unit& u, int wr, int wc, int fr, int fq) const {
;     ...
;                     const int row = rb + 128 * ai + 64 * wr + 16 * m + fr; const unsigned f = flags >> (3 * (ai * 4 + m));
;                     if (bstart) { if (f & 2u) { pA1 = zero; pG1 = zero; }
;                                   if (f & 4u) { pA2 = zero; pG2 = zero; } }
;                     const f32x2v va = wA0 * pA2 + wA1 * pA1 + wA2 * ua + bA, vg = wG0 * pG2 + wG1 * pG1 + wG2 * ug + bG;
;                     const float o0 = va[0] * __builtin_amdgcn_rcpf(1.f + __expf(-va[0])) * vg[0], o1 = va[1] * __builtin_amdgcn_rcpf(1.f + __expf(-va[1])) * vg[1];
;                     if (allemit) *(GAS unsigned*)(G + (size_t)row * 2816 + ca0) = pk2(o0, o1);
;                     else if (f & 1u) *(GAS unsigned*)(G + (size_t)row * 2816 + ca0) = pk2(o0, o1);
.LBB0_277:
	v_and_b32_e32 v67, 0x200000, v67
	v_cmp_ne_u32_e32 vcc, 0, v67
	s_or_b64 s[54:55], s[90:91], vcc
	s_and_saveexec_b64 s[52:53], s[54:55]
	s_cbranch_execz .LBB0_279
	s_waitcnt lgkmcnt(3)
	v_pk_mul_f32 v[144:145], v[144:145], v[200:201]
	s_waitcnt lgkmcnt(2)
	v_pk_fma_f32 v[132:133], v[132:133], v[196:197], v[144:145]
	s_waitcnt lgkmcnt(1)
	v_pk_fma_f32 v[132:133], v[150:151], v[136:137], v[132:133]
	s_waitcnt lgkmcnt(0)
	v_pk_add_f32 v[132:133], v[140:141], v[132:133]
	s_nop 0
	v_mul_f32_e32 v67, 0xbfb8aa3b, v133
	v_exp_f32_e32 v67, v67
	v_mul_f32_e32 v136, 0xbfb8aa3b, v132
	v_exp_f32_e32 v140, v136
	v_pk_mul_f32 v[136:137], v[146:147], v[198:199]
	v_add_f32_e32 v67, 1.0, v67
	v_rcp_f32_e32 v141, v67
	v_add_f32_e32 v67, 1.0, v140
	v_rcp_f32_e32 v140, v67
	v_pk_fma_f32 v[134:135], v[134:135], v[194:195], v[136:137]
	v_pk_mul_f32 v[132:133], v[132:133], v[140:141]
	v_pk_fma_f32 v[134:135], v[148:149], v[138:139], v[134:135]
	s_nop 0
	v_pk_add_f32 v[134:135], v[142:143], v[134:135]
	s_nop 0
	v_pk_mul_f32 v[132:133], v[134:135], v[132:133]
	s_nop 0
	v_cvt_pk_bf16_f32 v67, v132, v133
	v_add_u32_e32 v132, 0xf2000, v154
	global_store_dword v132, v67, s[86:87]

; #define GAS __attribute__((address_space(1)))
; __device__ __forceinline__ unsigned pk2(float lo, float hi) { f32x2v v = {lo, hi}; bf16x2v b = __builtin_convertvector(v, bf16x2v); return __builtin_bit_cast(unsigned, b); }
; #define GAS __attribute__((address_space(1)))
;     __device__ __forceinline__ void operator()(const f32x4 (&acc)[2][2][4][2], const Unit& u, int wr, int wc, int fr, int fq) const {
;     ...
;                     const int row = rb + 128 * ai + 64 * wr + 16 * m + fr; const unsigned f = flags >> (3 * (ai * 4 + m));
;                     if (bstart) { if (f & 2u) { pA1 = zero; pG1 = zero; }
;                                   if (f & 4u) { pA2 = zero; pG2 = zero; } }
;                     const f32x2v va = wA0 * pA2 + wA1 * pA1 + wA2 * ua + bA, vg = wG0 * pG2 + wG1 * pG1 + wG2 * ug + bG;
;                     const float o0 = va[0] * __builtin_amdgcn_rcpf(1.f + __expf(-va[0])) * vg[0], o1 = va[1] * __builtin_amdgcn_rcpf(1.f + __expf(-va[1])) * vg[1];
;                     if (allemit) *(GAS unsigned*)(G + (size_t)row * 2816 + ca0) = pk2(o0, o1);
;                     else if (f & 1u) *(GAS unsigned*)(G + (size_t)row * 2816 + ca0) = pk2(o0, o1);
.LBB0_286:
	s_and_saveexec_b64 s[52:53], s[84:85]
	s_cbranch_execz .LBB0_288
	s_waitcnt lgkmcnt(3)
	v_pk_mul_f32 v[200:201], v[144:145], v[200:201]
	s_waitcnt lgkmcnt(2)
	v_pk_fma_f32 v[196:197], v[132:133], v[196:197], v[200:201]
	s_waitcnt lgkmcnt(1)
	v_pk_fma_f32 v[150:151], v[150:151], v[136:137], v[196:197]
	v_pk_mul_f32 v[196:197], v[146:147], v[198:199]
	s_waitcnt lgkmcnt(0)
	v_pk_add_f32 v[150:151], v[140:141], v[150:151]
	v_pk_fma_f32 v[194:195], v[134:135], v[194:195], v[196:197]
	v_mul_f32_e32 v153, 0xbfb8aa3b, v151
	v_exp_f32_e32 v153, v153
	v_mul_f32_e32 v185, 0xbfb8aa3b, v150
	v_exp_f32_e32 v185, v185
	v_pk_fma_f32 v[148:149], v[148:149], v[138:139], v[194:195]
	v_add_f32_e32 v153, 1.0, v153
	v_rcp_f32_e32 v199, v153
	v_add_f32_e32 v153, 1.0, v185
	v_rcp_f32_e32 v198, v153
	v_pk_add_f32 v[148:149], v[142:143], v[148:149]
	v_pk_mul_f32 v[150:151], v[150:151], v[198:199]
	s_nop 0
	v_pk_mul_f32 v[148:149], v[148:149], v[150:151]
	s_nop 0
	v_cvt_pk_bf16_f32 v150, v148, v149
	s_nop 0
	global_store_dword v154, v150, s[86:87] offset:4

; #define GAS __attribute__((address_space(1)))
; __device__ __forceinline__ unsigned pk2(float lo, float hi) { f32x2v v = {lo, hi}; bf16x2v b = __builtin_convertvector(v, bf16x2v); return __builtin_bit_cast(unsigned, b); }
; #define GAS __attribute__((address_space(1)))
;     __device__ __forceinline__ void operator()(const f32x4 (&acc)[2][2][4][2], const Unit& u, int wr, int wc, int fr, int fq) const {
;     ...
;                     const int row = rb + 128 * ai + 64 * wr + 16 * m + fr; const unsigned f = flags >> (3 * (ai * 4 + m));
;                     if (bstart) { if (f & 2u) { pA1 = zero; pG1 = zero; }
;                                   if (f & 4u) { pA2 = zero; pG2 = zero; } }
;                     const f32x2v va = wA0 * pA2 + wA1 * pA1 + wA2 * ua + bA, vg = wG0 * pG2 + wG1 * pG1 + wG2 * ug + bG;
;                     const float o0 = va[0] * __builtin_amdgcn_rcpf(1.f + __expf(-va[0])) * vg[0], o1 = va[1] * __builtin_amdgcn_rcpf(1.f + __expf(-va[1])) * vg[1];
;                     if (allemit) *(GAS unsigned*)(G + (size_t)row * 2816 + ca0) = pk2(o0, o1);
;                     else if (f & 1u) *(GAS unsigned*)(G + (size_t)row * 2816 + ca0) = pk2(o0, o1);
.LBB0_292:
	s_and_saveexec_b64 s[52:53], s[62:63]
	s_cbranch_execz .LBB0_294
	s_waitcnt lgkmcnt(3)
	v_pk_mul_f32 v[200:201], v[144:145], v[200:201]
	s_waitcnt lgkmcnt(2)
	v_pk_fma_f32 v[196:197], v[132:133], v[196:197], v[200:201]
	s_waitcnt lgkmcnt(1)
	v_pk_fma_f32 v[150:151], v[150:151], v[136:137], v[196:197]
	v_pk_mul_f32 v[196:197], v[146:147], v[198:199]
	s_waitcnt lgkmcnt(0)
	v_pk_add_f32 v[150:151], v[140:141], v[150:151]
	v_pk_fma_f32 v[194:195], v[134:135], v[194:195], v[196:197]
	v_mul_f32_e32 v67, 0xbfb8aa3b, v151
	v_exp_f32_e32 v67, v67
	v_mul_f32_e32 v187, 0xbfb8aa3b, v150
	v_exp_f32_e32 v187, v187
	v_pk_fma_f32 v[148:149], v[148:149], v[138:139], v[194:195]
	v_add_f32_e32 v67, 1.0, v67
	v_rcp_f32_e32 v199, v67
	v_add_f32_e32 v67, 1.0, v187
	v_rcp_f32_e32 v198, v67
	v_pk_add_f32 v[148:149], v[142:143], v[148:149]
	v_pk_mul_f32 v[150:151], v[150:151], v[198:199]
	s_nop 0
	v_pk_mul_f32 v[148:149], v[148:149], v[150:151]
	s_nop 0
	v_cvt_pk_bf16_f32 v67, v148, v149
	v_add_u32_e32 v148, 0x16000, v154
	global_store_dword v148, v67, s[86:87] offset:4

; #define GAS __attribute__((address_space(1)))
; __device__ __forceinline__ unsigned pk2(float lo, float hi) { f32x2v v = {lo, hi}; bf16x2v b = __builtin_convertvector(v, bf16x2v); return __builtin_bit_cast(unsigned, b); }
; #define GAS __attribute__((address_space(1)))
;     __device__ __forceinline__ void operator()(const f32x4 (&acc)[2][2][4][2], const Unit& u, int wr, int wc, int fr, int fq) const {
;     ...
;                     const int row = rb + 128 * ai + 64 * wr + 16 * m + fr; const unsigned f = flags >> (3 * (ai * 4 + m));
;                     if (bstart) { if (f & 2u) { pA1 = zero; pG1 = zero; }
;                                   if (f & 4u) { pA2 = zero; pG2 = zero; } }
;                     const f32x2v va = wA0 * pA2 + wA1 * pA1 + wA2 * ua + bA, vg = wG0 * pG2 + wG1 * pG1 + wG2 * ug + bG;
;                     const float o0 = va[0] * __builtin_amdgcn_rcpf(1.f + __expf(-va[0])) * vg[0], o1 = va[1] * __builtin_amdgcn_rcpf(1.f + __expf(-va[1])) * vg[1];
;                     if (allemit) *(GAS unsigned*)(G + (size_t)row * 2816 + ca0) = pk2(o0, o1);
;                     else if (f & 1u) *(GAS unsigned*)(G + (size_t)row * 2816 + ca0) = pk2(o0, o1);
.LBB0_298:
	s_and_saveexec_b64 s[52:53], s[6:7]
	s_cbranch_execz .LBB0_300
	s_waitcnt lgkmcnt(3)
	v_pk_mul_f32 v[200:201], v[144:145], v[200:201]
	s_waitcnt lgkmcnt(2)
	v_pk_fma_f32 v[196:197], v[132:133], v[196:197], v[200:201]
	s_waitcnt lgkmcnt(1)
	v_pk_fma_f32 v[150:151], v[150:151], v[136:137], v[196:197]
	v_pk_mul_f32 v[196:197], v[146:147], v[198:199]
	s_waitcnt lgkmcnt(0)
	v_pk_add_f32 v[150:151], v[140:141], v[150:151]
	v_pk_fma_f32 v[194:195], v[134:135], v[194:195], v[196:197]
	v_mul_f32_e32 v153, 0xbfb8aa3b, v151
	v_exp_f32_e32 v153, v153
	v_mul_f32_e32 v191, 0xbfb8aa3b, v150
	v_exp_f32_e32 v191, v191
	v_pk_fma_f32 v[148:149], v[148:149], v[138:139], v[194:195]
	v_add_f32_e32 v153, 1.0, v153
	v_rcp_f32_e32 v199, v153
	v_add_f32_e32 v153, 1.0, v191
	v_rcp_f32_e32 v198, v153
	v_pk_add_f32 v[148:149], v[142:143], v[148:149]
	v_pk_mul_f32 v[150:151], v[150:151], v[198:199]
	s_nop 0
	v_pk_mul_f32 v[148:149], v[148:149], v[150:151]
	s_nop 0
	v_cvt_pk_bf16_f32 v150, v148, v149
	v_add_u32_e32 v148, 0x2c000, v154
	global_store_dword v148, v150, s[86:87] offset:4

; #define GAS __attribute__((address_space(1)))
; __device__ __forceinline__ unsigned pk2(float lo, float hi) { f32x2v v = {lo, hi}; bf16x2v b = __builtin_convertvector(v, bf16x2v); return __builtin_bit_cast(unsigned, b); }
; #define GAS __attribute__((address_space(1)))
;     __device__ __forceinline__ void operator()(const f32x4 (&acc)[2][2][4][2], const Unit& u, int wr, int wc, int fr, int fq) const {
;     ...
;                     const int row = rb + 128 * ai + 64 * wr + 16 * m + fr; const unsigned f = flags >> (3 * (ai * 4 + m));
;                     if (bstart) { if (f & 2u) { pA1 = zero; pG1 = zero; }
;                                   if (f & 4u) { pA2 = zero; pG2 = zero; } }
;                     const f32x2v va = wA0 * pA2 + wA1 * pA1 + wA2 * ua + bA, vg = wG0 * pG2 + wG1 * pG1 + wG2 * ug + bG;
;                     const float o0 = va[0] * __builtin_amdgcn_rcpf(1.f + __expf(-va[0])) * vg[0], o1 = va[1] * __builtin_amdgcn_rcpf(1.f + __expf(-va[1])) * vg[1];
;                     if (allemit) *(GAS unsigned*)(G + (size_t)row * 2816 + ca0) = pk2(o0, o1);
;                     else if (f & 1u) *(GAS unsigned*)(G + (size_t)row * 2816 + ca0) = pk2(o0, o1);
.LBB0_304:
	s_and_saveexec_b64 s[52:53], s[16:17]
	s_cbranch_execz .LBB0_306
	s_waitcnt lgkmcnt(3)
	v_pk_mul_f32 v[200:201], v[144:145], v[200:201]
	s_waitcnt lgkmcnt(2)
	v_pk_fma_f32 v[196:197], v[132:133], v[196:197], v[200:201]
	s_waitcnt lgkmcnt(1)
	v_pk_fma_f32 v[150:151], v[150:151], v[136:137], v[196:197]
	v_pk_mul_f32 v[196:197], v[146:147], v[198:199]
	s_waitcnt lgkmcnt(0)
	v_pk_add_f32 v[150:151], v[140:141], v[150:151]
	v_pk_fma_f32 v[194:195], v[134:135], v[194:195], v[196:197]
	v_mul_f32_e32 v67, 0xbfb8aa3b, v151
	v_exp_f32_e32 v67, v67
	v_mul_f32_e32 v189, 0xbfb8aa3b, v150
	v_exp_f32_e32 v189, v189
	v_pk_fma_f32 v[148:149], v[148:149], v[138:139], v[194:195]
	v_add_f32_e32 v67, 1.0, v67
	v_rcp_f32_e32 v199, v67
	v_add_f32_e32 v67, 1.0, v189
	v_rcp_f32_e32 v198, v67
	v_pk_add_f32 v[148:149], v[142:143], v[148:149]
	v_pk_mul_f32 v[150:151], v[150:151], v[198:199]
	s_nop 0
	v_pk_mul_f32 v[148:149], v[148:149], v[150:151]
	s_nop 0
	v_cvt_pk_bf16_f32 v67, v148, v149
	v_add_u32_e32 v148, 0x42000, v154
	global_store_dword v148, v67, s[86:87] offset:4

; #define GAS __attribute__((address_space(1)))
; __device__ __forceinline__ unsigned pk2(float lo, float hi) { f32x2v v = {lo, hi}; bf16x2v b = __builtin_convertvector(v, bf16x2v); return __builtin_bit_cast(unsigned, b); }
; #define GAS __attribute__((address_space(1)))
;     __device__ __forceinline__ void operator()(const f32x4 (&acc)[2][2][4][2], const Unit& u, int wr, int wc, int fr, int fq) const {
;     ...
;                     const int row = rb + 128 * ai + 64 * wr + 16 * m + fr; const unsigned f = flags >> (3 * (ai * 4 + m));
;                     if (bstart) { if (f & 2u) { pA1 = zero; pG1 = zero; }
;                                   if (f & 4u) { pA2 = zero; pG2 = zero; } }
;                     const f32x2v va = wA0 * pA2 + wA1 * pA1 + wA2 * ua + bA, vg = wG0 * pG2 + wG1 * pG1 + wG2 * ug + bG;
;                     const float o0 = va[0] * __builtin_amdgcn_rcpf(1.f + __expf(-va[0])) * vg[0], o1 = va[1] * __builtin_amdgcn_rcpf(1.f + __expf(-va[1])) * vg[1];
;                     if (allemit) *(GAS unsigned*)(G + (size_t)row * 2816 + ca0) = pk2(o0, o1);
;                     else if (f & 1u) *(GAS unsigned*)(G + (size_t)row * 2816 + ca0) = pk2(o0, o1);
.LBB0_312:
	s_and_saveexec_b64 s[52:53], s[58:59]
	s_cbranch_execz .LBB0_314
	s_waitcnt lgkmcnt(3)
	v_pk_mul_f32 v[200:201], v[144:145], v[200:201]
	v_pk_mul_f32 v[150:151], v[146:147], v[150:151]
	s_waitcnt lgkmcnt(2)
	v_pk_fma_f32 v[198:199], v[132:133], v[198:199], v[200:201]
	v_pk_fma_f32 v[148:149], v[134:135], v[148:149], v[150:151]
	s_waitcnt lgkmcnt(1)
	v_pk_fma_f32 v[196:197], v[196:197], v[136:137], v[198:199]
	v_pk_fma_f32 v[148:149], v[194:195], v[138:139], v[148:149]
	s_waitcnt lgkmcnt(0)
	v_pk_add_f32 v[196:197], v[140:141], v[196:197]
	v_pk_add_f32 v[148:149], v[142:143], v[148:149]
	v_mul_f32_e32 v191, 0xbfb8aa3b, v197
	v_exp_f32_e32 v191, v191
	v_mul_f32_e32 v198, 0xbfb8aa3b, v196
	v_exp_f32_e32 v198, v198
	v_add_f32_e32 v191, 1.0, v191
	v_rcp_f32_e32 v199, v191
	v_add_f32_e32 v191, 1.0, v198
	v_rcp_f32_e32 v198, v191
	s_nop 0
	v_pk_mul_f32 v[150:151], v[196:197], v[198:199]
	s_nop 0
	v_pk_mul_f32 v[148:149], v[148:149], v[150:151]
	s_nop 0
	v_cvt_pk_bf16_f32 v150, v148, v149
	v_add_u32_e32 v148, 0xb0000, v154
	global_store_dword v148, v150, s[86:87] offset:4

; #define GAS __attribute__((address_space(1)))
; __device__ __forceinline__ unsigned pk2(float lo, float hi) { f32x2v v = {lo, hi}; bf16x2v b = __builtin_convertvector(v, bf16x2v); return __builtin_bit_cast(unsigned, b); }
; #define GAS __attribute__((address_space(1)))
;     __device__ __forceinline__ void operator()(const f32x4 (&acc)[2][2][4][2], const Unit& u, int wr, int wc, int fr, int fq) const {
;     ...
;                     const int row = rb + 128 * ai + 64 * wr + 16 * m + fr; const unsigned f = flags >> (3 * (ai * 4 + m));
;                     if (bstart) { if (f & 2u) { pA1 = zero; pG1 = zero; }
;                                   if (f & 4u) { pA2 = zero; pG2 = zero; } }
;                     const f32x2v va = wA0 * pA2 + wA1 * pA1 + wA2 * ua + bA, vg = wG0 * pG2 + wG1 * pG1 + wG2 * ug + bG;
;                     const float o0 = va[0] * __builtin_amdgcn_rcpf(1.f + __expf(-va[0])) * vg[0], o1 = va[1] * __builtin_amdgcn_rcpf(1.f + __expf(-va[1])) * vg[1];
;                     if (allemit) *(GAS unsigned*)(G + (size_t)row * 2816 + ca0) = pk2(o0, o1);
;                     else if (f & 1u) *(GAS unsigned*)(G + (size_t)row * 2816 + ca0) = pk2(o0, o1);
.LBB0_318:
	s_and_saveexec_b64 s[52:53], s[56:57]
	s_cbranch_execz .LBB0_320
	s_waitcnt lgkmcnt(3)
	v_pk_mul_f32 v[200:201], v[144:145], v[200:201]
	s_waitcnt lgkmcnt(2)
	v_pk_fma_f32 v[196:197], v[132:133], v[196:197], v[200:201]
	s_waitcnt lgkmcnt(1)
	v_pk_fma_f32 v[150:151], v[150:151], v[136:137], v[196:197]
	v_pk_mul_f32 v[196:197], v[146:147], v[198:199]
	s_waitcnt lgkmcnt(0)
	v_pk_add_f32 v[150:151], v[140:141], v[150:151]
	v_pk_fma_f32 v[194:195], v[134:135], v[194:195], v[196:197]
	v_mul_f32_e32 v67, 0xbfb8aa3b, v151
	v_exp_f32_e32 v67, v67
	v_mul_f32_e32 v193, 0xbfb8aa3b, v150
	v_exp_f32_e32 v193, v193
	v_pk_fma_f32 v[148:149], v[148:149], v[138:139], v[194:195]
	v_add_f32_e32 v67, 1.0, v67
	v_rcp_f32_e32 v199, v67
	v_add_f32_e32 v67, 1.0, v193
	v_rcp_f32_e32 v198, v67
	v_pk_add_f32 v[148:149], v[142:143], v[148:149]
	v_pk_mul_f32 v[150:151], v[150:151], v[198:199]
	s_nop 0
	v_pk_mul_f32 v[148:149], v[148:149], v[150:151]
	s_nop 0
	v_cvt_pk_bf16_f32 v67, v148, v149
	v_add_u32_e32 v148, 0xc6000, v154
	global_store_dword v148, v67, s[86:87] offset:4

; #define GAS __attribute__((address_space(1)))
; __device__ __forceinline__ unsigned pk2(float lo, float hi) { f32x2v v = {lo, hi}; bf16x2v b = __builtin_convertvector(v, bf16x2v); return __builtin_bit_cast(unsigned, b); }
; #define GAS __attribute__((address_space(1)))
;     __device__ __forceinline__ void operator()(const f32x4 (&acc)[2][2][4][2], const Unit& u, int wr, int wc, int fr, int fq) const {
;     ...
;                     const int row = rb + 128 * ai + 64 * wr + 16 * m + fr; const unsigned f = flags >> (3 * (ai * 4 + m));
;                     if (bstart) { if (f & 2u) { pA1 = zero; pG1 = zero; }
;                                   if (f & 4u) { pA2 = zero; pG2 = zero; } }
;                     const f32x2v va = wA0 * pA2 + wA1 * pA1 + wA2 * ua + bA, vg = wG0 * pG2 + wG1 * pG1 + wG2 * ug + bG;
;                     const float o0 = va[0] * __builtin_amdgcn_rcpf(1.f + __expf(-va[0])) * vg[0], o1 = va[1] * __builtin_amdgcn_rcpf(1.f + __expf(-va[1])) * vg[1];
;                     if (allemit) *(GAS unsigned*)(G + (size_t)row * 2816 + ca0) = pk2(o0, o1);
;                     else if (f & 1u) *(GAS unsigned*)(G + (size_t)row * 2816 + ca0) = pk2(o0, o1);
.LBB0_324:
	s_and_saveexec_b64 s[52:53], s[68:69]
	s_cbranch_execz .LBB0_326
	s_waitcnt lgkmcnt(3)
	v_pk_mul_f32 v[200:201], v[144:145], v[200:201]
	s_waitcnt lgkmcnt(2)
	v_pk_fma_f32 v[196:197], v[132:133], v[196:197], v[200:201]
	s_waitcnt lgkmcnt(1)
	v_pk_fma_f32 v[150:151], v[150:151], v[136:137], v[196:197]
	s_waitcnt lgkmcnt(0)
	v_pk_add_f32 v[150:151], v[140:141], v[150:151]
	s_nop 0
	v_mul_f32_e32 v67, 0xbfb8aa3b, v151
	v_exp_f32_e32 v67, v67
	v_mul_f32_e32 v196, 0xbfb8aa3b, v150
	v_exp_f32_e32 v200, v196
	v_pk_mul_f32 v[196:197], v[146:147], v[198:199]
	v_add_f32_e32 v67, 1.0, v67
	v_rcp_f32_e32 v199, v67
	v_add_f32_e32 v67, 1.0, v200
	v_rcp_f32_e32 v198, v67
	v_pk_fma_f32 v[194:195], v[134:135], v[194:195], v[196:197]
	v_pk_mul_f32 v[150:151], v[150:151], v[198:199]
	v_pk_fma_f32 v[148:149], v[148:149], v[138:139], v[194:195]
	s_nop 0
	v_pk_add_f32 v[148:149], v[142:143], v[148:149]
	s_nop 0
	v_pk_mul_f32 v[148:149], v[148:149], v[150:151]
	s_nop 0
	v_cvt_pk_bf16_f32 v67, v148, v149
	v_add_u32_e32 v148, 0xdc000, v154
	global_store_dword v148, v67, s[86:87] offset:4

; #define GAS __attribute__((address_space(1)))
; __device__ __forceinline__ unsigned pk2(float lo, float hi) { f32x2v v = {lo, hi}; bf16x2v b = __builtin_convertvector(v, bf16x2v); return __builtin_bit_cast(unsigned, b); }
; #define GAS __attribute__((address_space(1)))
;     __device__ __forceinline__ void operator()(const f32x4 (&acc)[2][2][4][2], const Unit& u, int wr, int wc, int fr, int fq) const {
;     ...
;                     const int row = rb + 128 * ai + 64 * wr + 16 * m + fr; const unsigned f = flags >> (3 * (ai * 4 + m));
;                     if (bstart) { if (f & 2u) { pA1 = zero; pG1 = zero; }
;                                   if (f & 4u) { pA2 = zero; pG2 = zero; } }
;                     const f32x2v va = wA0 * pA2 + wA1 * pA1 + wA2 * ua + bA, vg = wG0 * pG2 + wG1 * pG1 + wG2 * ug + bG;
;                     const float o0 = va[0] * __builtin_amdgcn_rcpf(1.f + __expf(-va[0])) * vg[0], o1 = va[1] * __builtin_amdgcn_rcpf(1.f + __expf(-va[1])) * vg[1];
;                     if (allemit) *(GAS unsigned*)(G + (size_t)row * 2816 + ca0) = pk2(o0, o1);
;                     else if (f & 1u) *(GAS unsigned*)(G + (size_t)row * 2816 + ca0) = pk2(o0, o1);
.LBB0_330:
	s_and_saveexec_b64 s[52:53], s[54:55]
	s_cbranch_execz .LBB0_332
	s_waitcnt lgkmcnt(3)
	v_pk_mul_f32 v[144:145], v[144:145], v[200:201]
	s_waitcnt lgkmcnt(2)
	v_pk_fma_f32 v[132:133], v[132:133], v[196:197], v[144:145]
	s_waitcnt lgkmcnt(1)
	v_pk_fma_f32 v[132:133], v[150:151], v[136:137], v[132:133]
	s_waitcnt lgkmcnt(0)
	v_pk_add_f32 v[132:133], v[140:141], v[132:133]
	s_nop 0
	v_mul_f32_e32 v136, 0xbfb8aa3b, v133
	v_exp_f32_e32 v140, v136
	v_mul_f32_e32 v136, 0xbfb8aa3b, v132
	v_exp_f32_e32 v144, v136
	v_pk_mul_f32 v[136:137], v[146:147], v[198:199]
	v_add_f32_e32 v140, 1.0, v140
	v_rcp_f32_e32 v141, v140
	v_add_f32_e32 v140, 1.0, v144
	v_rcp_f32_e32 v140, v140
	v_pk_fma_f32 v[134:135], v[134:135], v[194:195], v[136:137]
	v_pk_mul_f32 v[132:133], v[132:133], v[140:141]
	v_pk_fma_f32 v[134:135], v[148:149], v[138:139], v[134:135]
	s_nop 0
	v_pk_add_f32 v[134:135], v[142:143], v[134:135]
	s_nop 0
	v_pk_mul_f32 v[132:133], v[134:135], v[132:133]
	s_nop 0
	v_cvt_pk_bf16_f32 v134, v132, v133
	v_add_u32_e32 v132, 0xf2000, v154
	global_store_dword v132, v134, s[86:87] offset:4

; #define GAS __attribute__((address_space(1)))
; __device__ __forceinline__ unsigned pk2(float lo, float hi) { f32x2v v = {lo, hi}; bf16x2v b = __builtin_convertvector(v, bf16x2v); return __builtin_bit_cast(unsigned, b); }
; #define GAS __attribute__((address_space(1)))
;     __device__ __forceinline__ void operator()(const f32x4 (&acc)[2][2][4][2], const Unit& u, int wr, int wc, int fr, int fq) const {
;     ...
;                     const int row = rb + 128 * ai + 64 * wr + 16 * m + fr; const unsigned f = flags >> (3 * (ai * 4 + m));
;                     if (bstart) { if (f & 2u) { pA1 = zero; pG1 = zero; }
;                                   if (f & 4u) { pA2 = zero; pG2 = zero; } }
;                     const f32x2v va = wA0 * pA2 + wA1 * pA1 + wA2 * ua + bA, vg = wG0 * pG2 + wG1 * pG1 + wG2 * ug + bG;
;                     const float o0 = va[0] * __builtin_amdgcn_rcpf(1.f + __expf(-va[0])) * vg[0], o1 = va[1] * __builtin_amdgcn_rcpf(1.f + __expf(-va[1])) * vg[1];
;                     if (allemit) *(GAS unsigned*)(G + (size_t)row * 2816 + ca0) = pk2(o0, o1);
;                     else if (f & 1u) *(GAS unsigned*)(G + (size_t)row * 2816 + ca0) = pk2(o0, o1);
.LBB0_339:
	s_and_saveexec_b64 s[52:53], s[84:85]
	s_cbranch_execz .LBB0_341
	s_waitcnt lgkmcnt(3)
	v_pk_mul_f32 v[200:201], v[144:145], v[200:201]
	s_waitcnt lgkmcnt(2)
	v_pk_fma_f32 v[196:197], v[132:133], v[196:197], v[200:201]
	s_waitcnt lgkmcnt(1)
	v_pk_fma_f32 v[150:151], v[150:151], v[136:137], v[196:197]
	s_waitcnt lgkmcnt(0)
	v_pk_add_f32 v[150:151], v[140:141], v[150:151]
	s_nop 0
	v_mul_f32_e32 v196, 0xbfb8aa3b, v151
	v_exp_f32_e32 v200, v196
	v_mul_f32_e32 v196, 0xbfb8aa3b, v150
	v_exp_f32_e32 v201, v196
	v_pk_mul_f32 v[196:197], v[146:147], v[198:199]
	v_add_f32_e32 v198, 1.0, v200
	v_rcp_f32_e32 v199, v198
	v_add_f32_e32 v198, 1.0, v201
	v_rcp_f32_e32 v198, v198
	v_pk_fma_f32 v[194:195], v[134:135], v[194:195], v[196:197]
	v_pk_mul_f32 v[150:151], v[150:151], v[198:199]
	v_pk_fma_f32 v[148:149], v[148:149], v[138:139], v[194:195]
	s_nop 0
	v_pk_add_f32 v[148:149], v[142:143], v[148:149]
	s_nop 0
	v_pk_mul_f32 v[148:149], v[148:149], v[150:151]
	s_nop 0
	v_cvt_pk_bf16_f32 v150, v148, v149
	s_nop 0
	global_store_dword v154, v150, s[86:87] offset:8

; #define GAS __attribute__((address_space(1)))
; __device__ __forceinline__ unsigned pk2(float lo, float hi) { f32x2v v = {lo, hi}; bf16x2v b = __builtin_convertvector(v, bf16x2v); return __builtin_bit_cast(unsigned, b); }
; #define GAS __attribute__((address_space(1)))
;     __device__ __forceinline__ void operator()(const f32x4 (&acc)[2][2][4][2], const Unit& u, int wr, int wc, int fr, int fq) const {
;     ...
;                     const int row = rb + 128 * ai + 64 * wr + 16 * m + fr; const unsigned f = flags >> (3 * (ai * 4 + m));
;                     if (bstart) { if (f & 2u) { pA1 = zero; pG1 = zero; }
;                                   if (f & 4u) { pA2 = zero; pG2 = zero; } }
;                     const f32x2v va = wA0 * pA2 + wA1 * pA1 + wA2 * ua + bA, vg = wG0 * pG2 + wG1 * pG1 + wG2 * ug + bG;
;                     const float o0 = va[0] * __builtin_amdgcn_rcpf(1.f + __expf(-va[0])) * vg[0], o1 = va[1] * __builtin_amdgcn_rcpf(1.f + __expf(-va[1])) * vg[1];
;                     if (allemit) *(GAS unsigned*)(G + (size_t)row * 2816 + ca0) = pk2(o0, o1);
;                     else if (f & 1u) *(GAS unsigned*)(G + (size_t)row * 2816 + ca0) = pk2(o0, o1);
.LBB0_345:
	s_and_saveexec_b64 s[52:53], s[62:63]
	s_cbranch_execz .LBB0_347
	s_waitcnt lgkmcnt(3)
	v_pk_mul_f32 v[200:201], v[144:145], v[200:201]
	s_waitcnt lgkmcnt(2)
	v_pk_fma_f32 v[196:197], v[132:133], v[196:197], v[200:201]
	s_waitcnt lgkmcnt(1)
	v_pk_fma_f32 v[150:151], v[150:151], v[136:137], v[196:197]
	s_waitcnt lgkmcnt(0)
	v_pk_add_f32 v[150:151], v[140:141], v[150:151]
	s_nop 0
	v_mul_f32_e32 v196, 0xbfb8aa3b, v151
	v_exp_f32_e32 v200, v196
	v_mul_f32_e32 v196, 0xbfb8aa3b, v150
	v_exp_f32_e32 v201, v196
	v_pk_mul_f32 v[196:197], v[146:147], v[198:199]
	v_add_f32_e32 v198, 1.0, v200
	v_rcp_f32_e32 v199, v198
	v_add_f32_e32 v198, 1.0, v201
	v_rcp_f32_e32 v198, v198
	v_pk_fma_f32 v[194:195], v[134:135], v[194:195], v[196:197]
	v_pk_mul_f32 v[150:151], v[150:151], v[198:199]
	v_pk_fma_f32 v[148:149], v[148:149], v[138:139], v[194:195]
	s_nop 0
	v_pk_add_f32 v[148:149], v[142:143], v[148:149]
	s_nop 0
	v_pk_mul_f32 v[148:149], v[148:149], v[150:151]
	s_nop 0
	v_cvt_pk_bf16_f32 v150, v148, v149
	v_add_u32_e32 v148, 0x16000, v154
	global_store_dword v148, v150, s[86:87] offset:8

; #define GAS __attribute__((address_space(1)))
; __device__ __forceinline__ unsigned pk2(float lo, float hi) { f32x2v v = {lo, hi}; bf16x2v b = __builtin_convertvector(v, bf16x2v); return __builtin_bit_cast(unsigned, b); }
; #define GAS __attribute__((address_space(1)))
;     __device__ __forceinline__ void operator()(const f32x4 (&acc)[2][2][4][2], const Unit& u, int wr, int wc, int fr, int fq) const {
;     ...
;                     const int row = rb + 128 * ai + 64 * wr + 16 * m + fr; const unsigned f = flags >> (3 * (ai * 4 + m));
;                     if (bstart) { if (f & 2u) { pA1 = zero; pG1 = zero; }
;                                   if (f & 4u) { pA2 = zero; pG2 = zero; } }
;                     const f32x2v va = wA0 * pA2 + wA1 * pA1 + wA2 * ua + bA, vg = wG0 * pG2 + wG1 * pG1 + wG2 * ug + bG;
;                     const float o0 = va[0] * __builtin_amdgcn_rcpf(1.f + __expf(-va[0])) * vg[0], o1 = va[1] * __builtin_amdgcn_rcpf(1.f + __expf(-va[1])) * vg[1];
;                     if (allemit) *(GAS unsigned*)(G + (size_t)row * 2816 + ca0) = pk2(o0, o1);
;                     else if (f & 1u) *(GAS unsigned*)(G + (size_t)row * 2816 + ca0) = pk2(o0, o1);
.LBB0_351:
	s_and_saveexec_b64 s[52:53], s[6:7]
	v_readlane_b32 s76, v253, 49
	v_readlane_b32 s77, v253, 50
	s_cbranch_execz .LBB0_353
	s_waitcnt lgkmcnt(3)
	v_pk_mul_f32 v[200:201], v[144:145], v[200:201]
	s_waitcnt lgkmcnt(2)
	v_pk_fma_f32 v[196:197], v[132:133], v[196:197], v[200:201]
	s_waitcnt lgkmcnt(1)
	v_pk_fma_f32 v[150:151], v[150:151], v[136:137], v[196:197]
	s_waitcnt lgkmcnt(0)
	v_pk_add_f32 v[150:151], v[140:141], v[150:151]
	s_nop 0
	v_mul_f32_e32 v196, 0xbfb8aa3b, v151
	v_exp_f32_e32 v200, v196
	v_mul_f32_e32 v196, 0xbfb8aa3b, v150
	v_exp_f32_e32 v201, v196
	v_pk_mul_f32 v[196:197], v[146:147], v[198:199]
	v_add_f32_e32 v198, 1.0, v200
	v_rcp_f32_e32 v199, v198
	v_add_f32_e32 v198, 1.0, v201
	v_rcp_f32_e32 v198, v198
	v_pk_fma_f32 v[194:195], v[134:135], v[194:195], v[196:197]
	v_pk_mul_f32 v[150:151], v[150:151], v[198:199]
	v_pk_fma_f32 v[148:149], v[148:149], v[138:139], v[194:195]
	s_nop 0
	v_pk_add_f32 v[148:149], v[142:143], v[148:149]
	s_nop 0
	v_pk_mul_f32 v[148:149], v[148:149], v[150:151]
	s_nop 0
	v_cvt_pk_bf16_f32 v150, v148, v149
	v_add_u32_e32 v148, 0x2c000, v154
	global_store_dword v148, v150, s[86:87] offset:8

; #define GAS __attribute__((address_space(1)))
; __device__ __forceinline__ unsigned pk2(float lo, float hi) { f32x2v v = {lo, hi}; bf16x2v b = __builtin_convertvector(v, bf16x2v); return __builtin_bit_cast(unsigned, b); }
; #define GAS __attribute__((address_space(1)))
;     __device__ __forceinline__ void operator()(const f32x4 (&acc)[2][2][4][2], const Unit& u, int wr, int wc, int fr, int fq) const {
;     ...
;                     const int row = rb + 128 * ai + 64 * wr + 16 * m + fr; const unsigned f = flags >> (3 * (ai * 4 + m));
;                     if (bstart) { if (f & 2u) { pA1 = zero; pG1 = zero; }
;                                   if (f & 4u) { pA2 = zero; pG2 = zero; } }
;                     const f32x2v va = wA0 * pA2 + wA1 * pA1 + wA2 * ua + bA, vg = wG0 * pG2 + wG1 * pG1 + wG2 * ug + bG;
;                     const float o0 = va[0] * __builtin_amdgcn_rcpf(1.f + __expf(-va[0])) * vg[0], o1 = va[1] * __builtin_amdgcn_rcpf(1.f + __expf(-va[1])) * vg[1];
;                     if (allemit) *(GAS unsigned*)(G + (size_t)row * 2816 + ca0) = pk2(o0, o1);
;                     else if (f & 1u) *(GAS unsigned*)(G + (size_t)row * 2816 + ca0) = pk2(o0, o1);
.LBB0_357:
	s_and_saveexec_b64 s[6:7], s[16:17]
	s_cbranch_execz .LBB0_359
	s_waitcnt lgkmcnt(3)
	v_pk_mul_f32 v[200:201], v[144:145], v[200:201]
	s_waitcnt lgkmcnt(2)
	v_pk_fma_f32 v[196:197], v[132:133], v[196:197], v[200:201]
	s_waitcnt lgkmcnt(1)
	v_pk_fma_f32 v[150:151], v[150:151], v[136:137], v[196:197]
	s_waitcnt lgkmcnt(0)
	v_pk_add_f32 v[150:151], v[140:141], v[150:151]
	s_nop 0
	v_mul_f32_e32 v196, 0xbfb8aa3b, v151
	v_exp_f32_e32 v200, v196
	v_mul_f32_e32 v196, 0xbfb8aa3b, v150
	v_exp_f32_e32 v201, v196
	v_pk_mul_f32 v[196:197], v[146:147], v[198:199]
	v_add_f32_e32 v198, 1.0, v200
	v_rcp_f32_e32 v199, v198
	v_add_f32_e32 v198, 1.0, v201
	v_rcp_f32_e32 v198, v198
	v_pk_fma_f32 v[194:195], v[134:135], v[194:195], v[196:197]
	v_pk_mul_f32 v[150:151], v[150:151], v[198:199]
	v_pk_fma_f32 v[148:149], v[148:149], v[138:139], v[194:195]
	s_nop 0
	v_pk_add_f32 v[148:149], v[142:143], v[148:149]
	s_nop 0
	v_pk_mul_f32 v[148:149], v[148:149], v[150:151]
	s_nop 0
	v_cvt_pk_bf16_f32 v150, v148, v149
	v_add_u32_e32 v148, 0x42000, v154
	global_store_dword v148, v150, s[86:87] offset:8

; #define GAS __attribute__((address_space(1)))
; __device__ __forceinline__ unsigned pk2(float lo, float hi) { f32x2v v = {lo, hi}; bf16x2v b = __builtin_convertvector(v, bf16x2v); return __builtin_bit_cast(unsigned, b); }
; #define GAS __attribute__((address_space(1)))
;     __device__ __forceinline__ void operator()(const f32x4 (&acc)[2][2][4][2], const Unit& u, int wr, int wc, int fr, int fq) const {
;     ...
;                     const int row = rb + 128 * ai + 64 * wr + 16 * m + fr; const unsigned f = flags >> (3 * (ai * 4 + m));
;                     if (bstart) { if (f & 2u) { pA1 = zero; pG1 = zero; }
;                                   if (f & 4u) { pA2 = zero; pG2 = zero; } }
;                     const f32x2v va = wA0 * pA2 + wA1 * pA1 + wA2 * ua + bA, vg = wG0 * pG2 + wG1 * pG1 + wG2 * ug + bG;
;                     const float o0 = va[0] * __builtin_amdgcn_rcpf(1.f + __expf(-va[0])) * vg[0], o1 = va[1] * __builtin_amdgcn_rcpf(1.f + __expf(-va[1])) * vg[1];
;                     if (allemit) *(GAS unsigned*)(G + (size_t)row * 2816 + ca0) = pk2(o0, o1);
;                     else if (f & 1u) *(GAS unsigned*)(G + (size_t)row * 2816 + ca0) = pk2(o0, o1);
.LBB0_365:
	s_and_saveexec_b64 s[6:7], s[58:59]
	s_cbranch_execz .LBB0_367
	s_waitcnt lgkmcnt(3)
	v_pk_mul_f32 v[200:201], v[144:145], v[200:201]
	v_pk_mul_f32 v[150:151], v[146:147], v[150:151]
	s_waitcnt lgkmcnt(2)
	v_pk_fma_f32 v[198:199], v[132:133], v[198:199], v[200:201]
	v_pk_fma_f32 v[148:149], v[134:135], v[148:149], v[150:151]
	s_waitcnt lgkmcnt(1)
	v_pk_fma_f32 v[196:197], v[196:197], v[136:137], v[198:199]
	v_pk_fma_f32 v[148:149], v[194:195], v[138:139], v[148:149]
	s_waitcnt lgkmcnt(0)
	v_pk_add_f32 v[196:197], v[140:141], v[196:197]
	v_pk_add_f32 v[148:149], v[142:143], v[148:149]
	v_mul_f32_e32 v198, 0xbfb8aa3b, v197
	v_exp_f32_e32 v198, v198
	v_mul_f32_e32 v199, 0xbfb8aa3b, v196
	v_exp_f32_e32 v200, v199
	v_add_f32_e32 v198, 1.0, v198
	v_rcp_f32_e32 v199, v198
	v_add_f32_e32 v198, 1.0, v200
	v_rcp_f32_e32 v198, v198
	s_nop 0
	v_pk_mul_f32 v[150:151], v[196:197], v[198:199]
	s_nop 0
	v_pk_mul_f32 v[148:149], v[148:149], v[150:151]
	s_nop 0
	v_cvt_pk_bf16_f32 v150, v148, v149
	v_add_u32_e32 v148, 0xb0000, v154
	global_store_dword v148, v150, s[86:87] offset:8

; #define GAS __attribute__((address_space(1)))
; __device__ __forceinline__ unsigned pk2(float lo, float hi) { f32x2v v = {lo, hi}; bf16x2v b = __builtin_convertvector(v, bf16x2v); return __builtin_bit_cast(unsigned, b); }
; #define GAS __attribute__((address_space(1)))
;     __device__ __forceinline__ void operator()(const f32x4 (&acc)[2][2][4][2], const Unit& u, int wr, int wc, int fr, int fq) const {
;     ...
;                     const int row = rb + 128 * ai + 64 * wr + 16 * m + fr; const unsigned f = flags >> (3 * (ai * 4 + m));
;                     if (bstart) { if (f & 2u) { pA1 = zero; pG1 = zero; }
;                                   if (f & 4u) { pA2 = zero; pG2 = zero; } }
;                     const f32x2v va = wA0 * pA2 + wA1 * pA1 + wA2 * ua + bA, vg = wG0 * pG2 + wG1 * pG1 + wG2 * ug + bG;
;                     const float o0 = va[0] * __builtin_amdgcn_rcpf(1.f + __expf(-va[0])) * vg[0], o1 = va[1] * __builtin_amdgcn_rcpf(1.f + __expf(-va[1])) * vg[1];
;                     if (allemit) *(GAS unsigned*)(G + (size_t)row * 2816 + ca0) = pk2(o0, o1);
;                     else if (f & 1u) *(GAS unsigned*)(G + (size_t)row * 2816 + ca0) = pk2(o0, o1);
.LBB0_371:
	s_and_saveexec_b64 s[6:7], s[56:57]
	s_cbranch_execz .LBB0_373
	s_waitcnt lgkmcnt(3)
	v_pk_mul_f32 v[200:201], v[144:145], v[200:201]
	s_waitcnt lgkmcnt(2)
	v_pk_fma_f32 v[196:197], v[132:133], v[196:197], v[200:201]
	s_waitcnt lgkmcnt(1)
	v_pk_fma_f32 v[150:151], v[150:151], v[136:137], v[196:197]
	s_waitcnt lgkmcnt(0)
	v_pk_add_f32 v[150:151], v[140:141], v[150:151]
	s_nop 0
	v_mul_f32_e32 v196, 0xbfb8aa3b, v151
	v_exp_f32_e32 v200, v196
	v_mul_f32_e32 v196, 0xbfb8aa3b, v150
	v_exp_f32_e32 v201, v196
	v_pk_mul_f32 v[196:197], v[146:147], v[198:199]
	v_add_f32_e32 v198, 1.0, v200
	v_rcp_f32_e32 v199, v198
	v_add_f32_e32 v198, 1.0, v201
	v_rcp_f32_e32 v198, v198
	v_pk_fma_f32 v[194:195], v[134:135], v[194:195], v[196:197]
	v_pk_mul_f32 v[150:151], v[150:151], v[198:199]
	v_pk_fma_f32 v[148:149], v[148:149], v[138:139], v[194:195]
	s_nop 0
	v_pk_add_f32 v[148:149], v[142:143], v[148:149]
	s_nop 0
	v_pk_mul_f32 v[148:149], v[148:149], v[150:151]
	s_nop 0
	v_cvt_pk_bf16_f32 v150, v148, v149
	v_add_u32_e32 v148, 0xc6000, v154
	global_store_dword v148, v150, s[86:87] offset:8

; #define GAS __attribute__((address_space(1)))
; __device__ __forceinline__ unsigned pk2(float lo, float hi) { f32x2v v = {lo, hi}; bf16x2v b = __builtin_convertvector(v, bf16x2v); return __builtin_bit_cast(unsigned, b); }
; #define GAS __attribute__((address_space(1)))
;     __device__ __forceinline__ void operator()(const f32x4 (&acc)[2][2][4][2], const Unit& u, int wr, int wc, int fr, int fq) const {
;     ...
;                     const int row = rb + 128 * ai + 64 * wr + 16 * m + fr; const unsigned f = flags >> (3 * (ai * 4 + m));
;                     if (bstart) { if (f & 2u) { pA1 = zero; pG1 = zero; }
;                                   if (f & 4u) { pA2 = zero; pG2 = zero; } }
;                     const f32x2v va = wA0 * pA2 + wA1 * pA1 + wA2 * ua + bA, vg = wG0 * pG2 + wG1 * pG1 + wG2 * ug + bG;
;                     const float o0 = va[0] * __builtin_amdgcn_rcpf(1.f + __expf(-va[0])) * vg[0], o1 = va[1] * __builtin_amdgcn_rcpf(1.f + __expf(-va[1])) * vg[1];
;                     if (allemit) *(GAS unsigned*)(G + (size_t)row * 2816 + ca0) = pk2(o0, o1);
;                     else if (f & 1u) *(GAS unsigned*)(G + (size_t)row * 2816 + ca0) = pk2(o0, o1);
.LBB0_377:
	s_and_saveexec_b64 s[6:7], s[68:69]
	s_cbranch_execz .LBB0_379
	s_waitcnt lgkmcnt(3)
	v_pk_mul_f32 v[200:201], v[144:145], v[200:201]
	s_waitcnt lgkmcnt(2)
	v_pk_fma_f32 v[196:197], v[132:133], v[196:197], v[200:201]
	s_waitcnt lgkmcnt(1)
	v_pk_fma_f32 v[150:151], v[150:151], v[136:137], v[196:197]
	s_waitcnt lgkmcnt(0)
	v_pk_add_f32 v[150:151], v[140:141], v[150:151]
	s_nop 0
	v_mul_f32_e32 v196, 0xbfb8aa3b, v151
	v_exp_f32_e32 v200, v196
	v_mul_f32_e32 v196, 0xbfb8aa3b, v150
	v_exp_f32_e32 v201, v196
	v_pk_mul_f32 v[196:197], v[146:147], v[198:199]
	v_add_f32_e32 v198, 1.0, v200
	v_rcp_f32_e32 v199, v198
	v_add_f32_e32 v198, 1.0, v201
	v_rcp_f32_e32 v198, v198
	v_pk_fma_f32 v[194:195], v[134:135], v[194:195], v[196:197]
	v_pk_mul_f32 v[150:151], v[150:151], v[198:199]
	v_pk_fma_f32 v[148:149], v[148:149], v[138:139], v[194:195]
	s_nop 0
	v_pk_add_f32 v[148:149], v[142:143], v[148:149]
	s_nop 0
	v_pk_mul_f32 v[148:149], v[148:149], v[150:151]
	s_nop 0
	v_cvt_pk_bf16_f32 v150, v148, v149
	v_add_u32_e32 v148, 0xdc000, v154
	global_store_dword v148, v150, s[86:87] offset:8

; #define GAS __attribute__((address_space(1)))
; __device__ __forceinline__ unsigned pk2(float lo, float hi) { f32x2v v = {lo, hi}; bf16x2v b = __builtin_convertvector(v, bf16x2v); return __builtin_bit_cast(unsigned, b); }
; #define GAS __attribute__((address_space(1)))
;     __device__ __forceinline__ void operator()(const f32x4 (&acc)[2][2][4][2], const Unit& u, int wr, int wc, int fr, int fq) const {
;     ...
;                     const int row = rb + 128 * ai + 64 * wr + 16 * m + fr; const unsigned f = flags >> (3 * (ai * 4 + m));
;                     if (bstart) { if (f & 2u) { pA1 = zero; pG1 = zero; }
;                                   if (f & 4u) { pA2 = zero; pG2 = zero; } }
;                     const f32x2v va = wA0 * pA2 + wA1 * pA1 + wA2 * ua + bA, vg = wG0 * pG2 + wG1 * pG1 + wG2 * ug + bG;
;                     const float o0 = va[0] * __builtin_amdgcn_rcpf(1.f + __expf(-va[0])) * vg[0], o1 = va[1] * __builtin_amdgcn_rcpf(1.f + __expf(-va[1])) * vg[1];
;                     if (allemit) *(GAS unsigned*)(G + (size_t)row * 2816 + ca0) = pk2(o0, o1);
;                     else if (f & 1u) *(GAS unsigned*)(G + (size_t)row * 2816 + ca0) = pk2(o0, o1);
.LBB0_383:
	s_and_saveexec_b64 s[6:7], s[54:55]
	s_cbranch_execz .LBB0_385
	s_waitcnt lgkmcnt(3)
	v_pk_mul_f32 v[144:145], v[144:145], v[200:201]
	s_waitcnt lgkmcnt(2)
	v_pk_fma_f32 v[132:133], v[132:133], v[196:197], v[144:145]
	s_waitcnt lgkmcnt(1)
	v_pk_fma_f32 v[132:133], v[150:151], v[136:137], v[132:133]
	s_waitcnt lgkmcnt(0)
	v_pk_add_f32 v[132:133], v[140:141], v[132:133]
	s_nop 0
	v_mul_f32_e32 v136, 0xbfb8aa3b, v133
	v_exp_f32_e32 v140, v136
	v_mul_f32_e32 v136, 0xbfb8aa3b, v132
	v_exp_f32_e32 v144, v136
	v_pk_mul_f32 v[136:137], v[146:147], v[198:199]
	v_add_f32_e32 v140, 1.0, v140
	v_rcp_f32_e32 v141, v140
	v_add_f32_e32 v140, 1.0, v144
	v_rcp_f32_e32 v140, v140
	v_pk_fma_f32 v[134:135], v[134:135], v[194:195], v[136:137]
	v_pk_mul_f32 v[132:133], v[132:133], v[140:141]
	v_pk_fma_f32 v[134:135], v[148:149], v[138:139], v[134:135]
	s_nop 0
	v_pk_add_f32 v[134:135], v[142:143], v[134:135]
	s_nop 0
	v_pk_mul_f32 v[132:133], v[134:135], v[132:133]
	s_nop 0
	v_cvt_pk_bf16_f32 v134, v132, v133
	v_add_u32_e32 v132, 0xf2000, v154
	global_store_dword v132, v134, s[86:87] offset:8

; #define GAS __attribute__((address_space(1)))
; __device__ __forceinline__ unsigned pk2(float lo, float hi) { f32x2v v = {lo, hi}; bf16x2v b = __builtin_convertvector(v, bf16x2v); return __builtin_bit_cast(unsigned, b); }
; #define GAS __attribute__((address_space(1)))
;     __device__ __forceinline__ void operator()(const f32x4 (&acc)[2][2][4][2], const Unit& u, int wr, int wc, int fr, int fq) const {
;     ...
;                     const int row = rb + 128 * ai + 64 * wr + 16 * m + fr; const unsigned f = flags >> (3 * (ai * 4 + m));
;                     if (bstart) { if (f & 2u) { pA1 = zero; pG1 = zero; }
;                                   if (f & 4u) { pA2 = zero; pG2 = zero; } }
;                     const f32x2v va = wA0 * pA2 + wA1 * pA1 + wA2 * ua + bA, vg = wG0 * pG2 + wG1 * pG1 + wG2 * ug + bG;
;                     const float o0 = va[0] * __builtin_amdgcn_rcpf(1.f + __expf(-va[0])) * vg[0], o1 = va[1] * __builtin_amdgcn_rcpf(1.f + __expf(-va[1])) * vg[1];
;                     if (allemit) *(GAS unsigned*)(G + (size_t)row * 2816 + ca0) = pk2(o0, o1);
;                     else if (f & 1u) *(GAS unsigned*)(G + (size_t)row * 2816 + ca0) = pk2(o0, o1);
.LBB0_392:
	s_and_saveexec_b64 s[6:7], s[84:85]
	s_cbranch_execz .LBB0_394
	s_waitcnt lgkmcnt(3)
	v_pk_mul_f32 v[198:199], v[144:145], v[198:199]
	s_waitcnt lgkmcnt(2)
	v_pk_fma_f32 v[194:195], v[132:133], v[194:195], v[198:199]
	s_waitcnt lgkmcnt(1)
	v_pk_fma_f32 v[150:151], v[150:151], v[136:137], v[194:195]
	s_waitcnt lgkmcnt(0)
	v_pk_add_f32 v[150:151], v[140:141], v[150:151]
	s_nop 0
	v_mul_f32_e32 v194, 0xbfb8aa3b, v151
	v_exp_f32_e32 v198, v194
	v_mul_f32_e32 v194, 0xbfb8aa3b, v150
	v_exp_f32_e32 v199, v194
	v_pk_mul_f32 v[194:195], v[146:147], v[196:197]
	v_add_f32_e32 v196, 1.0, v198
	v_rcp_f32_e32 v197, v196
	v_add_f32_e32 v196, 1.0, v199
	v_rcp_f32_e32 v196, v196
	v_pk_fma_f32 v[182:183], v[134:135], v[182:183], v[194:195]
	v_pk_mul_f32 v[150:151], v[150:151], v[196:197]
	v_pk_fma_f32 v[148:149], v[148:149], v[138:139], v[182:183]
	s_nop 0
	v_pk_add_f32 v[148:149], v[142:143], v[148:149]
	s_nop 0
	v_pk_mul_f32 v[148:149], v[148:149], v[150:151]
	s_nop 0
	v_cvt_pk_bf16_f32 v150, v148, v149
	s_nop 0
	global_store_dword v154, v150, s[86:87] offset:12

; #define GAS __attribute__((address_space(1)))
; __device__ __forceinline__ unsigned pk2(float lo, float hi) { f32x2v v = {lo, hi}; bf16x2v b = __builtin_convertvector(v, bf16x2v); return __builtin_bit_cast(unsigned, b); }
; #define GAS __attribute__((address_space(1)))
;     __device__ __forceinline__ void operator()(const f32x4 (&acc)[2][2][4][2], const Unit& u, int wr, int wc, int fr, int fq) const {
;     ...
;                     const int row = rb + 128 * ai + 64 * wr + 16 * m + fr; const unsigned f = flags >> (3 * (ai * 4 + m));
;                     if (bstart) { if (f & 2u) { pA1 = zero; pG1 = zero; }
;                                   if (f & 4u) { pA2 = zero; pG2 = zero; } }
;                     const f32x2v va = wA0 * pA2 + wA1 * pA1 + wA2 * ua + bA, vg = wG0 * pG2 + wG1 * pG1 + wG2 * ug + bG;
;                     const float o0 = va[0] * __builtin_amdgcn_rcpf(1.f + __expf(-va[0])) * vg[0], o1 = va[1] * __builtin_amdgcn_rcpf(1.f + __expf(-va[1])) * vg[1];
;                     if (allemit) *(GAS unsigned*)(G + (size_t)row * 2816 + ca0) = pk2(o0, o1);
;                     else if (f & 1u) *(GAS unsigned*)(G + (size_t)row * 2816 + ca0) = pk2(o0, o1);
.LBB0_398:
	s_and_saveexec_b64 s[6:7], s[62:63]
	s_cbranch_execz .LBB0_400
	s_waitcnt lgkmcnt(3)
	v_pk_mul_f32 v[196:197], v[144:145], v[196:197]
	s_waitcnt lgkmcnt(2)
	v_pk_fma_f32 v[184:185], v[132:133], v[184:185], v[196:197]
	s_waitcnt lgkmcnt(1)
	v_pk_fma_f32 v[150:151], v[150:151], v[136:137], v[184:185]
	s_waitcnt lgkmcnt(0)
	v_pk_add_f32 v[150:151], v[140:141], v[150:151]
	s_nop 0
	v_mul_f32_e32 v184, 0xbfb8aa3b, v151
	v_exp_f32_e32 v196, v184
	v_mul_f32_e32 v184, 0xbfb8aa3b, v150
	v_exp_f32_e32 v197, v184
	v_pk_mul_f32 v[184:185], v[146:147], v[194:195]
	v_add_f32_e32 v194, 1.0, v196
	v_rcp_f32_e32 v195, v194
	v_add_f32_e32 v194, 1.0, v197
	v_rcp_f32_e32 v194, v194
	v_pk_fma_f32 v[182:183], v[134:135], v[182:183], v[184:185]
	v_pk_mul_f32 v[150:151], v[150:151], v[194:195]
	v_pk_fma_f32 v[148:149], v[148:149], v[138:139], v[182:183]
	s_nop 0
	v_pk_add_f32 v[148:149], v[142:143], v[148:149]
	s_nop 0
	v_pk_mul_f32 v[148:149], v[148:149], v[150:151]
	s_nop 0
	v_cvt_pk_bf16_f32 v150, v148, v149
	v_add_u32_e32 v148, 0x16000, v154
	global_store_dword v148, v150, s[86:87] offset:12

; #define GAS __attribute__((address_space(1)))
; __device__ __forceinline__ unsigned pk2(float lo, float hi) { f32x2v v = {lo, hi}; bf16x2v b = __builtin_convertvector(v, bf16x2v); return __builtin_bit_cast(unsigned, b); }
; #define GAS __attribute__((address_space(1)))
;     __device__ __forceinline__ void operator()(const f32x4 (&acc)[2][2][4][2], const Unit& u, int wr, int wc, int fr, int fq) const {
;     ...
;                     const int row = rb + 128 * ai + 64 * wr + 16 * m + fr; const unsigned f = flags >> (3 * (ai * 4 + m));
;                     if (bstart) { if (f & 2u) { pA1 = zero; pG1 = zero; }
;                                   if (f & 4u) { pA2 = zero; pG2 = zero; } }
;                     const f32x2v va = wA0 * pA2 + wA1 * pA1 + wA2 * ua + bA, vg = wG0 * pG2 + wG1 * pG1 + wG2 * ug + bG;
;                     const float o0 = va[0] * __builtin_amdgcn_rcpf(1.f + __expf(-va[0])) * vg[0], o1 = va[1] * __builtin_amdgcn_rcpf(1.f + __expf(-va[1])) * vg[1];
;                     if (allemit) *(GAS unsigned*)(G + (size_t)row * 2816 + ca0) = pk2(o0, o1);
;                     else if (f & 1u) *(GAS unsigned*)(G + (size_t)row * 2816 + ca0) = pk2(o0, o1);
.LBB0_404:
	v_and_b32_e32 v198, 64, v222
	v_cmp_ne_u32_e32 vcc, 0, v198
	s_or_b64 s[16:17], s[90:91], vcc
	s_and_saveexec_b64 s[6:7], s[16:17]
	s_cbranch_execz .LBB0_406
	s_waitcnt lgkmcnt(3)
	v_pk_mul_f32 v[194:195], v[144:145], v[194:195]
	s_waitcnt lgkmcnt(2)
	v_pk_fma_f32 v[184:185], v[132:133], v[184:185], v[194:195]
	s_waitcnt lgkmcnt(1)
	v_pk_fma_f32 v[150:151], v[150:151], v[136:137], v[184:185]
	s_waitcnt lgkmcnt(0)
	v_pk_add_f32 v[150:151], v[140:141], v[150:151]
	s_nop 0
	v_mul_f32_e32 v184, 0xbfb8aa3b, v151
	v_exp_f32_e32 v194, v184
	v_mul_f32_e32 v184, 0xbfb8aa3b, v150
	v_exp_f32_e32 v195, v184
	v_pk_mul_f32 v[184:185], v[146:147], v[186:187]
	v_add_f32_e32 v186, 1.0, v194
	v_rcp_f32_e32 v187, v186
	v_add_f32_e32 v186, 1.0, v195
	v_rcp_f32_e32 v186, v186
	v_pk_fma_f32 v[182:183], v[134:135], v[182:183], v[184:185]
	v_pk_mul_f32 v[150:151], v[150:151], v[186:187]
	v_pk_fma_f32 v[148:149], v[148:149], v[138:139], v[182:183]
	s_nop 0
	v_pk_add_f32 v[148:149], v[142:143], v[148:149]
	s_nop 0
	v_pk_mul_f32 v[148:149], v[148:149], v[150:151]
	s_nop 0
	v_cvt_pk_bf16_f32 v150, v148, v149
	v_add_u32_e32 v148, 0x2c000, v154
	global_store_dword v148, v150, s[86:87] offset:12

; #define GAS __attribute__((address_space(1)))
; __device__ __forceinline__ unsigned pk2(float lo, float hi) { f32x2v v = {lo, hi}; bf16x2v b = __builtin_convertvector(v, bf16x2v); return __builtin_bit_cast(unsigned, b); }
; #define GAS __attribute__((address_space(1)))
;     __device__ __forceinline__ void operator()(const f32x4 (&acc)[2][2][4][2], const Unit& u, int wr, int wc, int fr, int fq) const {
;     ...
;                     const int row = rb + 128 * ai + 64 * wr + 16 * m + fr; const unsigned f = flags >> (3 * (ai * 4 + m));
;                     if (bstart) { if (f & 2u) { pA1 = zero; pG1 = zero; }
;                                   if (f & 4u) { pA2 = zero; pG2 = zero; } }
;                     const f32x2v va = wA0 * pA2 + wA1 * pA1 + wA2 * ua + bA, vg = wG0 * pG2 + wG1 * pG1 + wG2 * ug + bG;
;                     const float o0 = va[0] * __builtin_amdgcn_rcpf(1.f + __expf(-va[0])) * vg[0], o1 = va[1] * __builtin_amdgcn_rcpf(1.f + __expf(-va[1])) * vg[1];
;                     if (allemit) *(GAS unsigned*)(G + (size_t)row * 2816 + ca0) = pk2(o0, o1);
;                     else if (f & 1u) *(GAS unsigned*)(G + (size_t)row * 2816 + ca0) = pk2(o0, o1);
.LBB0_410:
	v_and_b32_e32 v194, 0x200, v221
	v_cmp_ne_u32_e32 vcc, 0, v194
	s_or_b64 s[16:17], s[90:91], vcc
	s_and_saveexec_b64 s[6:7], s[16:17]
	s_movk_i32 s91, 0x1600
	s_cbranch_execz .LBB0_412
	s_waitcnt lgkmcnt(3)
	v_pk_mul_f32 v[186:187], v[144:145], v[186:187]
	s_waitcnt lgkmcnt(2)
	v_pk_fma_f32 v[182:183], v[132:133], v[182:183], v[186:187]
	s_waitcnt lgkmcnt(1)
	v_pk_fma_f32 v[150:151], v[150:151], v[136:137], v[182:183]
	s_waitcnt lgkmcnt(0)
	v_pk_add_f32 v[150:151], v[140:141], v[150:151]
	s_nop 0
	v_mul_f32_e32 v182, 0xbfb8aa3b, v151
	v_exp_f32_e32 v186, v182
	v_mul_f32_e32 v182, 0xbfb8aa3b, v150
	v_exp_f32_e32 v187, v182
	v_pk_mul_f32 v[182:183], v[146:147], v[184:185]
	v_add_f32_e32 v184, 1.0, v186
	v_rcp_f32_e32 v185, v184
	v_add_f32_e32 v184, 1.0, v187
	v_rcp_f32_e32 v184, v184
	v_pk_fma_f32 v[152:153], v[134:135], v[152:153], v[182:183]
	v_pk_mul_f32 v[150:151], v[150:151], v[184:185]
	v_pk_fma_f32 v[148:149], v[148:149], v[138:139], v[152:153]
	s_nop 0
	v_pk_add_f32 v[148:149], v[142:143], v[148:149]
	s_nop 0
	v_pk_mul_f32 v[148:149], v[148:149], v[150:151]
	s_nop 0
	v_cvt_pk_bf16_f32 v150, v148, v149
	v_add_u32_e32 v148, 0x42000, v154
	global_store_dword v148, v150, s[86:87] offset:12

; #define GAS __attribute__((address_space(1)))
; __device__ __forceinline__ unsigned pk2(float lo, float hi) { f32x2v v = {lo, hi}; bf16x2v b = __builtin_convertvector(v, bf16x2v); return __builtin_bit_cast(unsigned, b); }
; #define GAS __attribute__((address_space(1)))
;     __device__ __forceinline__ void operator()(const f32x4 (&acc)[2][2][4][2], const Unit& u, int wr, int wc, int fr, int fq) const {
;     ...
;                     const int row = rb + 128 * ai + 64 * wr + 16 * m + fr; const unsigned f = flags >> (3 * (ai * 4 + m));
;                     if (bstart) { if (f & 2u) { pA1 = zero; pG1 = zero; }
;                                   if (f & 4u) { pA2 = zero; pG2 = zero; } }
;                     const f32x2v va = wA0 * pA2 + wA1 * pA1 + wA2 * ua + bA, vg = wG0 * pG2 + wG1 * pG1 + wG2 * ug + bG;
;                     const float o0 = va[0] * __builtin_amdgcn_rcpf(1.f + __expf(-va[0])) * vg[0], o1 = va[1] * __builtin_amdgcn_rcpf(1.f + __expf(-va[1])) * vg[1];
;                     if (allemit) *(GAS unsigned*)(G + (size_t)row * 2816 + ca0) = pk2(o0, o1);
;                     else if (f & 1u) *(GAS unsigned*)(G + (size_t)row * 2816 + ca0) = pk2(o0, o1);
.LBB0_418:
	s_and_saveexec_b64 s[6:7], s[58:59]
	s_cbranch_execz .LBB0_420
	s_waitcnt lgkmcnt(3)
	v_pk_mul_f32 v[186:187], v[144:145], v[186:187]
	v_pk_mul_f32 v[150:151], v[146:147], v[150:151]
	s_waitcnt lgkmcnt(2)
	v_pk_fma_f32 v[184:185], v[132:133], v[184:185], v[186:187]
	v_pk_fma_f32 v[148:149], v[134:135], v[148:149], v[150:151]
	s_waitcnt lgkmcnt(1)
	v_pk_fma_f32 v[182:183], v[182:183], v[136:137], v[184:185]
	v_pk_fma_f32 v[148:149], v[152:153], v[138:139], v[148:149]
	s_waitcnt lgkmcnt(0)
	v_pk_add_f32 v[182:183], v[140:141], v[182:183]
	v_pk_add_f32 v[148:149], v[142:143], v[148:149]
	v_mul_f32_e32 v184, 0xbfb8aa3b, v183
	v_exp_f32_e32 v184, v184
	v_mul_f32_e32 v185, 0xbfb8aa3b, v182
	v_exp_f32_e32 v186, v185
	v_add_f32_e32 v184, 1.0, v184
	v_rcp_f32_e32 v185, v184
	v_add_f32_e32 v184, 1.0, v186
	v_rcp_f32_e32 v184, v184
	s_nop 0
	v_pk_mul_f32 v[150:151], v[182:183], v[184:185]
	s_nop 0
	v_pk_mul_f32 v[148:149], v[148:149], v[150:151]
	s_nop 0
	v_cvt_pk_bf16_f32 v150, v148, v149
	v_add_u32_e32 v148, 0xb0000, v154
	global_store_dword v148, v150, s[86:87] offset:12

; #define GAS __attribute__((address_space(1)))
; __device__ __forceinline__ unsigned pk2(float lo, float hi) { f32x2v v = {lo, hi}; bf16x2v b = __builtin_convertvector(v, bf16x2v); return __builtin_bit_cast(unsigned, b); }
; #define GAS __attribute__((address_space(1)))
;     __device__ __forceinline__ void operator()(const f32x4 (&acc)[2][2][4][2], const Unit& u, int wr, int wc, int fr, int fq) const {
;     ...
;                     const int row = rb + 128 * ai + 64 * wr + 16 * m + fr; const unsigned f = flags >> (3 * (ai * 4 + m));
;                     if (bstart) { if (f & 2u) { pA1 = zero; pG1 = zero; }
;                                   if (f & 4u) { pA2 = zero; pG2 = zero; } }
;                     const f32x2v va = wA0 * pA2 + wA1 * pA1 + wA2 * ua + bA, vg = wG0 * pG2 + wG1 * pG1 + wG2 * ug + bG;
;                     const float o0 = va[0] * __builtin_amdgcn_rcpf(1.f + __expf(-va[0])) * vg[0], o1 = va[1] * __builtin_amdgcn_rcpf(1.f + __expf(-va[1])) * vg[1];
;                     if (allemit) *(GAS unsigned*)(G + (size_t)row * 2816 + ca0) = pk2(o0, o1);
;                     else if (f & 1u) *(GAS unsigned*)(G + (size_t)row * 2816 + ca0) = pk2(o0, o1);
.LBB0_424:
	s_and_saveexec_b64 s[6:7], s[56:57]
	s_cbranch_execz .LBB0_426
	s_waitcnt lgkmcnt(3)
	v_pk_mul_f32 v[186:187], v[144:145], v[186:187]
	s_waitcnt lgkmcnt(2)
	v_pk_fma_f32 v[182:183], v[132:133], v[182:183], v[186:187]
	s_waitcnt lgkmcnt(1)
	v_pk_fma_f32 v[150:151], v[150:151], v[136:137], v[182:183]
	s_waitcnt lgkmcnt(0)
	v_pk_add_f32 v[150:151], v[140:141], v[150:151]
	s_nop 0
	v_mul_f32_e32 v182, 0xbfb8aa3b, v151
	v_exp_f32_e32 v186, v182
	v_mul_f32_e32 v182, 0xbfb8aa3b, v150
	v_exp_f32_e32 v187, v182
	v_pk_mul_f32 v[182:183], v[146:147], v[184:185]
	v_add_f32_e32 v184, 1.0, v186
	v_rcp_f32_e32 v185, v184
	v_add_f32_e32 v184, 1.0, v187
	v_rcp_f32_e32 v184, v184
	v_pk_fma_f32 v[152:153], v[134:135], v[152:153], v[182:183]
	v_pk_mul_f32 v[150:151], v[150:151], v[184:185]
	v_pk_fma_f32 v[148:149], v[148:149], v[138:139], v[152:153]
	s_nop 0
	v_pk_add_f32 v[148:149], v[142:143], v[148:149]
	s_nop 0
	v_pk_mul_f32 v[148:149], v[148:149], v[150:151]
	s_nop 0
	v_cvt_pk_bf16_f32 v150, v148, v149
	v_add_u32_e32 v148, 0xc6000, v154
	global_store_dword v148, v150, s[86:87] offset:12

; #define GAS __attribute__((address_space(1)))
; __device__ __forceinline__ unsigned pk2(float lo, float hi) { f32x2v v = {lo, hi}; bf16x2v b = __builtin_convertvector(v, bf16x2v); return __builtin_bit_cast(unsigned, b); }
; #define GAS __attribute__((address_space(1)))
;     __device__ __forceinline__ void operator()(const f32x4 (&acc)[2][2][4][2], const Unit& u, int wr, int wc, int fr, int fq) const {
;     ...
;                     const int row = rb + 128 * ai + 64 * wr + 16 * m + fr; const unsigned f = flags >> (3 * (ai * 4 + m));
;                     if (bstart) { if (f & 2u) { pA1 = zero; pG1 = zero; }
;                                   if (f & 4u) { pA2 = zero; pG2 = zero; } }
;                     const f32x2v va = wA0 * pA2 + wA1 * pA1 + wA2 * ua + bA, vg = wG0 * pG2 + wG1 * pG1 + wG2 * ug + bG;
;                     const float o0 = va[0] * __builtin_amdgcn_rcpf(1.f + __expf(-va[0])) * vg[0], o1 = va[1] * __builtin_amdgcn_rcpf(1.f + __expf(-va[1])) * vg[1];
;                     if (allemit) *(GAS unsigned*)(G + (size_t)row * 2816 + ca0) = pk2(o0, o1);
;                     else if (f & 1u) *(GAS unsigned*)(G + (size_t)row * 2816 + ca0) = pk2(o0, o1);
.LBB0_430:
	s_and_saveexec_b64 s[6:7], s[68:69]
	s_cbranch_execz .LBB0_432
	s_waitcnt lgkmcnt(3)
	v_pk_mul_f32 v[186:187], v[144:145], v[186:187]
	s_waitcnt lgkmcnt(2)
	v_pk_fma_f32 v[182:183], v[132:133], v[182:183], v[186:187]
	s_waitcnt lgkmcnt(1)
	v_pk_fma_f32 v[150:151], v[150:151], v[136:137], v[182:183]
	s_waitcnt lgkmcnt(0)
	v_pk_add_f32 v[150:151], v[140:141], v[150:151]
	s_nop 0
	v_mul_f32_e32 v182, 0xbfb8aa3b, v151
	v_exp_f32_e32 v186, v182
	v_mul_f32_e32 v182, 0xbfb8aa3b, v150
	v_exp_f32_e32 v187, v182
	v_pk_mul_f32 v[182:183], v[146:147], v[184:185]
	v_add_f32_e32 v184, 1.0, v186
	v_rcp_f32_e32 v185, v184
	v_add_f32_e32 v184, 1.0, v187
	v_rcp_f32_e32 v184, v184
	v_pk_fma_f32 v[152:153], v[134:135], v[152:153], v[182:183]
	v_pk_mul_f32 v[150:151], v[150:151], v[184:185]
	v_pk_fma_f32 v[148:149], v[148:149], v[138:139], v[152:153]
	s_nop 0
	v_pk_add_f32 v[148:149], v[142:143], v[148:149]
	s_nop 0
	v_pk_mul_f32 v[148:149], v[148:149], v[150:151]
	s_nop 0
	v_cvt_pk_bf16_f32 v150, v148, v149
	v_add_u32_e32 v148, 0xdc000, v154
	global_store_dword v148, v150, s[86:87] offset:12

; #define GAS __attribute__((address_space(1)))
; __device__ __forceinline__ unsigned pk2(float lo, float hi) { f32x2v v = {lo, hi}; bf16x2v b = __builtin_convertvector(v, bf16x2v); return __builtin_bit_cast(unsigned, b); }
; #define GAS __attribute__((address_space(1)))
;     __device__ __forceinline__ void operator()(const f32x4 (&acc)[2][2][4][2], const Unit& u, int wr, int wc, int fr, int fq) const {
;     ...
;                     const int row = rb + 128 * ai + 64 * wr + 16 * m + fr; const unsigned f = flags >> (3 * (ai * 4 + m));
;                     if (bstart) { if (f & 2u) { pA1 = zero; pG1 = zero; }
;                                   if (f & 4u) { pA2 = zero; pG2 = zero; } }
;                     const f32x2v va = wA0 * pA2 + wA1 * pA1 + wA2 * ua + bA, vg = wG0 * pG2 + wG1 * pG1 + wG2 * ug + bG;
;                     const float o0 = va[0] * __builtin_amdgcn_rcpf(1.f + __expf(-va[0])) * vg[0], o1 = va[1] * __builtin_amdgcn_rcpf(1.f + __expf(-va[1])) * vg[1];
;                     if (allemit) *(GAS unsigned*)(G + (size_t)row * 2816 + ca0) = pk2(o0, o1);
;                     else if (f & 1u) *(GAS unsigned*)(G + (size_t)row * 2816 + ca0) = pk2(o0, o1);
.LBB0_436:
	s_and_saveexec_b64 s[6:7], s[54:55]
	s_cbranch_execz .LBB0_438
	s_waitcnt lgkmcnt(3)
	v_pk_mul_f32 v[144:145], v[144:145], v[184:185]
	s_waitcnt lgkmcnt(2)
	v_pk_fma_f32 v[132:133], v[132:133], v[152:153], v[144:145]
	s_waitcnt lgkmcnt(1)
	v_pk_fma_f32 v[132:133], v[148:149], v[136:137], v[132:133]
	s_waitcnt lgkmcnt(0)
	v_pk_add_f32 v[132:133], v[140:141], v[132:133]
	s_nop 0
	v_mul_f32_e32 v136, 0xbfb8aa3b, v133
	v_exp_f32_e32 v140, v136
	v_mul_f32_e32 v136, 0xbfb8aa3b, v132
	v_exp_f32_e32 v144, v136
	v_pk_mul_f32 v[136:137], v[146:147], v[182:183]
	v_add_f32_e32 v140, 1.0, v140
	v_rcp_f32_e32 v141, v140
	v_add_f32_e32 v140, 1.0, v144
	v_rcp_f32_e32 v140, v140
	v_pk_fma_f32 v[134:135], v[134:135], v[150:151], v[136:137]
	v_pk_mul_f32 v[132:133], v[132:133], v[140:141]
	v_pk_fma_f32 v[66:67], v[66:67], v[138:139], v[134:135]
	s_nop 0
	v_pk_add_f32 v[66:67], v[142:143], v[66:67]
	s_nop 0
	v_pk_mul_f32 v[66:67], v[66:67], v[132:133]
	s_nop 0
	v_cvt_pk_bf16_f32 v132, v66, v67
	v_add_u32_e32 v66, 0xf2000, v154
	global_store_dword v66, v132, s[86:87] offset:12
